# v20 plus the redundant mid-block s_setprio 0/1 pairs removed from the four GEMM K-loops
# speedup vs baseline: 1.0101x; 1.0101x over previous
; #define PG8_STAGE(bufoff, gbase, voff) do { _Pragma("unroll") for (int _i = 0; _i < 2; ++_i) \
;         __builtin_amdgcn_global_load_lds((const unsigned*)((const char*)(gbase) + (voff)[_i]), (LAS unsigned*)(lds + (bufoff) + ldsw + _i * 8192), 16, 0, 0); } while (0)
; #define PG8_LDA(dst, b, h) do { _Pragma("unroll") for (int m = 0; m < 4; ++m) _Pragma("unroll") for (int k = 0; k < 2; ++k) dst[m][k] = *(const LAS bf16x8*)(lds + PG8_SA(b, h) + aoff + m * 2048 + k * 1024); } while (0)
; #define PG8_LDB(dst, b, h) do { _Pragma("unroll") for (int n = 0; n < 2; ++n) _Pragma("unroll") for (int k = 0; k < 2; ++k) dst[n][k] = *(const LAS bf16x8*)(lds + PG8_SB(b, h) + boff + n * 2048 + k * 1024); } while (0)
; #define PG8_MMA(ai, bj, At, Bt) do { __builtin_amdgcn_s_setprio(1); _Pragma("unroll") for (int m = 0; m < 4; ++m) _Pragma("unroll") for (int n = 0; n < 2; ++n) _Pragma("unroll") for (int k = 0; k < 2; ++k) \
;         acc[ai][bj][m][n] = __builtin_amdgcn_mfma_f32_16x16x32_bf16(Bt[n][k], At[m][k], acc[ai][bj][m][n], 0, 0, 0); __builtin_amdgcn_s_setprio(0); } while (0)
; #define PG8_WAIT_V(n) asm volatile("s_waitcnt vmcnt(" #n ")" ::: "memory")
; #define PG8_WAIT_L(n) asm volatile("s_waitcnt lgkmcnt(" #n ")" ::: "memory")
; #define PG8_BAR __builtin_amdgcn_s_barrier()
; #define PG8_SCHED __builtin_amdgcn_sched_barrier(0)
; template <class Epi, class Sched>
; __device__ __forceinline__ void gemm_phase(LAS unsigned char* lds, const Gemm g, const Sched& S, const Epi& E, const int wid) {
;     ...
;         for (int t = 0; t < nt; t += 2) {
;             const bool last = (t == nt - 2);
;             const char* a1 = cA + (size_t)(t + 1) * kstep;
;             const char* a2 = last ? nA : cA + (size_t)(t + 2) * kstep; const char* b2 = last ? nB : cB + (size_t)(t + 2) * kstep;
;             const char* a3 = a2 + kstep; const char* b3 = b2 + kstep;
;             PG8_LDB(B0, 0, 0); PG8_LDB(B1, 0, 1); PG8_SCHED; PG8_LDA(At, 0, 0); PG8_STAGE(PG8_SA(1, 1), a1 + hstepA, voffA);
;             PG8_WAIT_V(8); PG8_WAIT_L(0); PG8_BAR; PG8_MMA(0, 0, At, B0); PG8_MMA(0, 1, At, B1); PG8_BAR; PG8_SCHED;
;             PG8_LDA(At, 0, 1); PG8_STAGE(PG8_SB(0, 0), b2, voffB); PG8_STAGE(PG8_SB(0, 1), b2 + hstepB, voffB); PG8_STAGE(PG8_SA(0, 0), a2, voffA);
;             PG8_WAIT_V(8); PG8_WAIT_L(0); PG8_BAR; PG8_MMA(1, 0, At, B0); PG8_MMA(1, 1, At, B1); PG8_BAR; PG8_SCHED;
.LBB0_247:
	v_add_u32_e32 v144, s76, v171
	ds_read_b128 v[128:131], v144
	ds_read_b128 v[132:135], v144 offset:1024
	ds_read_b128 v[192:195], v144 offset:2048
	ds_read_b128 v[196:199], v144 offset:3072
	v_add_u32_e32 v144, s77, v171
	ds_read_b128 v[200:203], v144
	ds_read_b128 v[204:207], v144 offset:1024
	ds_read_b128 v[208:211], v144 offset:2048
	ds_read_b128 v[212:215], v144 offset:3072
	s_add_u32 s58, s56, 0xfffc0080
	s_addc_u32 s59, s57, -1
	s_cmp_eq_u32 s86, 12
	s_cselect_b32 s61, s16, s59
	s_cselect_b32 s60, s47, s58
	s_cselect_b32 s59, s45, s85
	s_cselect_b32 s58, s53, s84
	v_lshl_add_u64 v[168:169], s[56:57], 0, v[160:161]
	s_add_i32 m0, s55, 0xc000
	ds_read_b128 v[216:219], v188
	ds_read_b128 v[220:223], v188 offset:1024
	ds_read_b128 v[224:227], v188 offset:2048
	ds_read_b128 v[228:231], v188 offset:3072
	ds_read_b128 v[232:235], v188 offset:4096
	ds_read_b128 v[236:239], v188 offset:5120
	ds_read_b128 v[240:243], v188 offset:6144
	ds_read_b128 v[244:247], v188 offset:7168
	global_load_lds_dwordx4 v[168:169], off
	v_lshl_add_u64 v[168:169], s[56:57], 0, v[162:163]
	s_add_i32 m0, s55, 0xe000
	s_nop 0
	global_load_lds_dwordx4 v[168:169], off
	s_waitcnt vmcnt(8)
	s_waitcnt lgkmcnt(0)
	s_barrier
	s_setprio 1
	s_waitcnt lgkmcnt(0)
	v_mfma_f32_16x16x32_bf16 v[124:127], v[128:131], v[216:219], v[124:127]
	v_mfma_f32_16x16x32_bf16 v[120:123], v[192:195], v[216:219], v[120:123]
	v_mfma_f32_16x16x32_bf16 v[108:111], v[128:131], v[224:227], v[108:111]
	v_mfma_f32_16x16x32_bf16 v[104:107], v[192:195], v[224:227], v[104:107]
	v_mfma_f32_16x16x32_bf16 v[92:95], v[128:131], v[232:235], v[92:95]
	v_mfma_f32_16x16x32_bf16 v[88:91], v[192:195], v[232:235], v[88:91]
	v_mfma_f32_16x16x32_bf16 v[76:79], v[128:131], v[240:243], v[76:79]
	v_mfma_f32_16x16x32_bf16 v[72:75], v[192:195], v[240:243], v[72:75]
	v_mfma_f32_16x16x32_bf16 v[124:127], v[132:135], v[220:223], v[124:127]
	v_mfma_f32_16x16x32_bf16 v[120:123], v[196:199], v[220:223], v[120:123]
	v_mfma_f32_16x16x32_bf16 v[108:111], v[132:135], v[228:231], v[108:111]
	v_mfma_f32_16x16x32_bf16 v[104:107], v[196:199], v[228:231], v[104:107]
	v_mfma_f32_16x16x32_bf16 v[92:95], v[132:135], v[236:239], v[92:95]
	v_mfma_f32_16x16x32_bf16 v[88:91], v[196:199], v[236:239], v[88:91]
	v_mfma_f32_16x16x32_bf16 v[76:79], v[132:135], v[244:247], v[76:79]
	v_mfma_f32_16x16x32_bf16 v[72:75], v[196:199], v[244:247], v[72:75]
	v_mfma_f32_16x16x32_bf16 v[116:119], v[200:203], v[216:219], v[116:119]
	v_mfma_f32_16x16x32_bf16 v[112:115], v[208:211], v[216:219], v[112:115]
	v_mfma_f32_16x16x32_bf16 v[100:103], v[200:203], v[224:227], v[100:103]
	v_mfma_f32_16x16x32_bf16 v[96:99], v[208:211], v[224:227], v[96:99]
	v_mfma_f32_16x16x32_bf16 v[84:87], v[200:203], v[232:235], v[84:87]
	v_mfma_f32_16x16x32_bf16 v[80:83], v[208:211], v[232:235], v[80:83]
	v_mfma_f32_16x16x32_bf16 v[68:71], v[200:203], v[240:243], v[68:71]
	v_mfma_f32_16x16x32_bf16 v[64:67], v[208:211], v[240:243], v[64:67]
	v_mfma_f32_16x16x32_bf16 v[116:119], v[204:207], v[220:223], v[116:119]
	v_mfma_f32_16x16x32_bf16 v[112:115], v[212:215], v[220:223], v[112:115]
	v_mfma_f32_16x16x32_bf16 v[100:103], v[204:207], v[228:231], v[100:103]
	v_mfma_f32_16x16x32_bf16 v[96:99], v[212:215], v[228:231], v[96:99]
	v_mfma_f32_16x16x32_bf16 v[84:87], v[204:207], v[236:239], v[84:87]
	v_mfma_f32_16x16x32_bf16 v[80:83], v[212:215], v[236:239], v[80:83]
	v_mfma_f32_16x16x32_bf16 v[68:71], v[204:207], v[244:247], v[68:71]
	v_mfma_f32_16x16x32_bf16 v[64:67], v[212:215], v[244:247], v[64:67]
	s_setprio 0
	s_barrier
	s_add_i32 s87, s76, s65
	v_lshl_add_u64 v[168:169], s[58:59], 0, v[138:139]
	s_mov_b32 m0, s87
	ds_read_b128 v[216:219], v188 offset:16384
	ds_read_b128 v[220:223], v188 offset:17408
	ds_read_b128 v[224:227], v188 offset:18432
	ds_read_b128 v[228:231], v188 offset:19456
	ds_read_b128 v[232:235], v188 offset:20480
	ds_read_b128 v[236:239], v188 offset:21504
	ds_read_b128 v[240:243], v188 offset:22528
	ds_read_b128 v[244:247], v188 offset:23552
	global_load_lds_dwordx4 v[168:169], off
	s_add_i32 m0, s87, 0x2000
	s_add_u32 s88, s58, 0x40000
	v_lshl_add_u64 v[248:249], s[58:59], 0, v[142:143]
	s_addc_u32 s89, s59, 0
	s_add_i32 s87, s77, s65
	global_load_lds_dwordx4 v[248:249], off
	v_lshl_add_u64 v[250:251], s[88:89], 0, v[138:139]
	s_mov_b32 m0, s87
	v_lshl_add_u64 v[252:253], s[60:61], 0, v[140:141]
	global_load_lds_dwordx4 v[250:251], off
	v_lshl_add_u64 v[250:251], s[88:89], 0, v[142:143]
	s_add_i32 m0, s87, 0x2000
	s_nop 0
	global_load_lds_dwordx4 v[250:251], off
	v_lshl_add_u64 v[250:251], s[60:61], 0, v[136:137]
	s_mov_b32 m0, s55
	s_nop 0
	global_load_lds_dwordx4 v[250:251], off
	s_mov_b32 m0, s66
	s_nop 0
	global_load_lds_dwordx4 v[252:253], off
	s_waitcnt vmcnt(8)
	s_waitcnt lgkmcnt(0)
	s_barrier
; #define PG8_STAGE(bufoff, gbase, voff) do { _Pragma("unroll") for (int _i = 0; _i < 2; ++_i) \
;         __builtin_amdgcn_global_load_lds((const unsigned*)((const char*)(gbase) + (voff)[_i]), (LAS unsigned*)(lds + (bufoff) + ldsw + _i * 8192), 16, 0, 0); } while (0)
; #define PG8_LDA(dst, b, h) do { _Pragma("unroll") for (int m = 0; m < 4; ++m) _Pragma("unroll") for (int k = 0; k < 2; ++k) dst[m][k] = *(const LAS bf16x8*)(lds + PG8_SA(b, h) + aoff + m * 2048 + k * 1024); } while (0)
; #define PG8_LDB(dst, b, h) do { _Pragma("unroll") for (int n = 0; n < 2; ++n) _Pragma("unroll") for (int k = 0; k < 2; ++k) dst[n][k] = *(const LAS bf16x8*)(lds + PG8_SB(b, h) + boff + n * 2048 + k * 1024); } while (0)
; #define PG8_MMA(ai, bj, At, Bt) do { __builtin_amdgcn_s_setprio(1); _Pragma("unroll") for (int m = 0; m < 4; ++m) _Pragma("unroll") for (int n = 0; n < 2; ++n) _Pragma("unroll") for (int k = 0; k < 2; ++k) \
;         acc[ai][bj][m][n] = __builtin_amdgcn_mfma_f32_16x16x32_bf16(Bt[n][k], At[m][k], acc[ai][bj][m][n], 0, 0, 0); __builtin_amdgcn_s_setprio(0); } while (0)
; #define PG8_WAIT_V(n) asm volatile("s_waitcnt vmcnt(" #n ")" ::: "memory")
; #define PG8_WAIT_L(n) asm volatile("s_waitcnt lgkmcnt(" #n ")" ::: "memory")
; #define PG8_BAR __builtin_amdgcn_s_barrier()
; #define PG8_SCHED __builtin_amdgcn_sched_barrier(0)
; template <class Epi, class Sched>
; __device__ __forceinline__ void gemm_phase(LAS unsigned char* lds, const Gemm g, const Sched& S, const Epi& E, const int wid) {
;     ...
;             PG8_WAIT_V(8); PG8_WAIT_L(0); PG8_BAR; PG8_MMA(1, 0, At, B0); PG8_MMA(1, 1, At, B1); PG8_BAR; PG8_SCHED;
;             PG8_LDB(B0, 1, 0); PG8_LDB(B1, 1, 1); PG8_SCHED; PG8_LDA(At, 1, 0); PG8_STAGE(PG8_SA(0, 1), a2 + hstepA, voffA);
;             PG8_WAIT_V(8); PG8_WAIT_L(0); PG8_BAR; PG8_MMA(0, 0, At, B0); PG8_MMA(0, 1, At, B1); PG8_BAR; PG8_SCHED;
	s_setprio 1
	s_waitcnt lgkmcnt(0)
	v_mfma_f32_16x16x32_bf16 v[60:63], v[128:131], v[216:219], v[60:63]
	v_mfma_f32_16x16x32_bf16 v[56:59], v[192:195], v[216:219], v[56:59]
	v_mfma_f32_16x16x32_bf16 v[44:47], v[128:131], v[224:227], v[44:47]
	v_mfma_f32_16x16x32_bf16 v[40:43], v[192:195], v[224:227], v[40:43]
	v_mfma_f32_16x16x32_bf16 v[28:31], v[128:131], v[232:235], v[28:31]
	v_mfma_f32_16x16x32_bf16 v[24:27], v[192:195], v[232:235], v[24:27]
	v_mfma_f32_16x16x32_bf16 v[12:15], v[128:131], v[240:243], v[12:15]
	v_mfma_f32_16x16x32_bf16 v[8:11], v[192:195], v[240:243], v[8:11]
	v_mfma_f32_16x16x32_bf16 v[60:63], v[132:135], v[220:223], v[60:63]
	v_mfma_f32_16x16x32_bf16 v[56:59], v[196:199], v[220:223], v[56:59]
	v_mfma_f32_16x16x32_bf16 v[44:47], v[132:135], v[228:231], v[44:47]
	v_mfma_f32_16x16x32_bf16 v[40:43], v[196:199], v[228:231], v[40:43]
	v_mfma_f32_16x16x32_bf16 v[28:31], v[132:135], v[236:239], v[28:31]
	v_mfma_f32_16x16x32_bf16 v[24:27], v[196:199], v[236:239], v[24:27]
	v_mfma_f32_16x16x32_bf16 v[12:15], v[132:135], v[244:247], v[12:15]
	v_mfma_f32_16x16x32_bf16 v[8:11], v[196:199], v[244:247], v[8:11]
	v_mfma_f32_16x16x32_bf16 v[52:55], v[200:203], v[216:219], v[52:55]
	v_mfma_f32_16x16x32_bf16 v[48:51], v[208:211], v[216:219], v[48:51]
	v_mfma_f32_16x16x32_bf16 v[36:39], v[200:203], v[224:227], v[36:39]
	v_mfma_f32_16x16x32_bf16 v[32:35], v[208:211], v[224:227], v[32:35]
	v_mfma_f32_16x16x32_bf16 v[20:23], v[200:203], v[232:235], v[20:23]
	v_mfma_f32_16x16x32_bf16 v[16:19], v[208:211], v[232:235], v[16:19]
	v_mfma_f32_16x16x32_bf16 v[4:7], v[200:203], v[240:243], v[4:7]
	v_mfma_f32_16x16x32_bf16 v[0:3], v[208:211], v[240:243], v[0:3]
	v_mfma_f32_16x16x32_bf16 v[52:55], v[204:207], v[220:223], v[52:55]
	v_mfma_f32_16x16x32_bf16 v[48:51], v[212:215], v[220:223], v[48:51]
	v_mfma_f32_16x16x32_bf16 v[36:39], v[204:207], v[228:231], v[36:39]
	v_mfma_f32_16x16x32_bf16 v[32:35], v[212:215], v[228:231], v[32:35]
	v_mfma_f32_16x16x32_bf16 v[20:23], v[204:207], v[236:239], v[20:23]
	v_mfma_f32_16x16x32_bf16 v[16:19], v[212:215], v[236:239], v[16:19]
	v_mfma_f32_16x16x32_bf16 v[4:7], v[204:207], v[244:247], v[4:7]
	v_mfma_f32_16x16x32_bf16 v[0:3], v[212:215], v[244:247], v[0:3]
	s_setprio 0
	s_barrier
	s_add_i32 s87, 0, 0x18000
	v_add_u32_e32 v144, s87, v171
	s_add_i32 s88, 0, 0x1c000
	ds_read_b128 v[128:131], v144
	ds_read_b128 v[132:135], v144 offset:1024
	ds_read_b128 v[192:195], v144 offset:2048
	ds_read_b128 v[196:199], v144 offset:3072
	v_add_u32_e32 v144, s88, v171
	ds_read_b128 v[200:203], v144
	ds_read_b128 v[204:207], v144 offset:1024
	ds_read_b128 v[208:211], v144 offset:2048
	ds_read_b128 v[212:215], v144 offset:3072
	s_add_u32 s60, s60, 0x40000
	s_addc_u32 s61, s61, 0
	s_mov_b32 m0, s67
	v_lshl_add_u64 v[254:255], s[60:61], 0, v[136:137]
	ds_read_b128 v[216:219], v188 offset:32768
	ds_read_b128 v[220:223], v188 offset:33792
	ds_read_b128 v[224:227], v188 offset:34816
	ds_read_b128 v[228:231], v188 offset:35840
	ds_read_b128 v[232:235], v188 offset:36864
	ds_read_b128 v[236:239], v188 offset:37888
	ds_read_b128 v[240:243], v188 offset:38912
	ds_read_b128 v[244:247], v188 offset:39936
	global_load_lds_dwordx4 v[254:255], off
	v_lshl_add_u64 v[254:255], s[60:61], 0, v[140:141]
	s_mov_b32 m0, s68
	s_nop 0
	global_load_lds_dwordx4 v[254:255], off
	s_waitcnt vmcnt(8)
	s_waitcnt lgkmcnt(0)
	s_barrier
	s_setprio 1
	s_waitcnt lgkmcnt(0)
	v_mfma_f32_16x16x32_bf16 v[124:127], v[128:131], v[216:219], v[124:127]
	v_mfma_f32_16x16x32_bf16 v[120:123], v[192:195], v[216:219], v[120:123]
	v_mfma_f32_16x16x32_bf16 v[108:111], v[128:131], v[224:227], v[108:111]
	v_mfma_f32_16x16x32_bf16 v[104:107], v[192:195], v[224:227], v[104:107]
	v_mfma_f32_16x16x32_bf16 v[92:95], v[128:131], v[232:235], v[92:95]
	v_mfma_f32_16x16x32_bf16 v[88:91], v[192:195], v[232:235], v[88:91]
	v_mfma_f32_16x16x32_bf16 v[76:79], v[128:131], v[240:243], v[76:79]
	v_mfma_f32_16x16x32_bf16 v[72:75], v[192:195], v[240:243], v[72:75]
	v_mfma_f32_16x16x32_bf16 v[124:127], v[132:135], v[220:223], v[124:127]
	v_mfma_f32_16x16x32_bf16 v[120:123], v[196:199], v[220:223], v[120:123]
	v_mfma_f32_16x16x32_bf16 v[108:111], v[132:135], v[228:231], v[108:111]
	v_mfma_f32_16x16x32_bf16 v[104:107], v[196:199], v[228:231], v[104:107]
	v_mfma_f32_16x16x32_bf16 v[92:95], v[132:135], v[236:239], v[92:95]
	v_mfma_f32_16x16x32_bf16 v[88:91], v[196:199], v[236:239], v[88:91]
	v_mfma_f32_16x16x32_bf16 v[76:79], v[132:135], v[244:247], v[76:79]
	v_mfma_f32_16x16x32_bf16 v[72:75], v[196:199], v[244:247], v[72:75]
	v_mfma_f32_16x16x32_bf16 v[116:119], v[200:203], v[216:219], v[116:119]
	v_mfma_f32_16x16x32_bf16 v[112:115], v[208:211], v[216:219], v[112:115]
	v_mfma_f32_16x16x32_bf16 v[100:103], v[200:203], v[224:227], v[100:103]
	v_mfma_f32_16x16x32_bf16 v[96:99], v[208:211], v[224:227], v[96:99]
	v_mfma_f32_16x16x32_bf16 v[84:87], v[200:203], v[232:235], v[84:87]
	v_mfma_f32_16x16x32_bf16 v[80:83], v[208:211], v[232:235], v[80:83]
	v_mfma_f32_16x16x32_bf16 v[68:71], v[200:203], v[240:243], v[68:71]
	v_mfma_f32_16x16x32_bf16 v[64:67], v[208:211], v[240:243], v[64:67]
	v_mfma_f32_16x16x32_bf16 v[116:119], v[204:207], v[220:223], v[116:119]
	v_mfma_f32_16x16x32_bf16 v[112:115], v[212:215], v[220:223], v[112:115]
	v_mfma_f32_16x16x32_bf16 v[100:103], v[204:207], v[228:231], v[100:103]
	v_mfma_f32_16x16x32_bf16 v[96:99], v[212:215], v[228:231], v[96:99]
	v_mfma_f32_16x16x32_bf16 v[84:87], v[204:207], v[236:239], v[84:87]
	v_mfma_f32_16x16x32_bf16 v[80:83], v[212:215], v[236:239], v[80:83]
	v_mfma_f32_16x16x32_bf16 v[68:71], v[204:207], v[244:247], v[68:71]
	v_mfma_f32_16x16x32_bf16 v[64:67], v[212:215], v[244:247], v[64:67]
	s_setprio 0
	s_barrier
; #define PG8_STAGE(bufoff, gbase, voff) do { _Pragma("unroll") for (int _i = 0; _i < 2; ++_i) \
;         __builtin_amdgcn_global_load_lds((const unsigned*)((const char*)(gbase) + (voff)[_i]), (LAS unsigned*)(lds + (bufoff) + ldsw + _i * 8192), 16, 0, 0); } while (0)
; #define PG8_LDA(dst, b, h) do { _Pragma("unroll") for (int m = 0; m < 4; ++m) _Pragma("unroll") for (int k = 0; k < 2; ++k) dst[m][k] = *(const LAS bf16x8*)(lds + PG8_SA(b, h) + aoff + m * 2048 + k * 1024); } while (0)
; #define PG8_MMA(ai, bj, At, Bt) do { __builtin_amdgcn_s_setprio(1); _Pragma("unroll") for (int m = 0; m < 4; ++m) _Pragma("unroll") for (int n = 0; n < 2; ++n) _Pragma("unroll") for (int k = 0; k < 2; ++k) \
;         acc[ai][bj][m][n] = __builtin_amdgcn_mfma_f32_16x16x32_bf16(Bt[n][k], At[m][k], acc[ai][bj][m][n], 0, 0, 0); __builtin_amdgcn_s_setprio(0); } while (0)
; #define PG8_WAIT_V(n) asm volatile("s_waitcnt vmcnt(" #n ")" ::: "memory")
; #define PG8_WAIT_L(n) asm volatile("s_waitcnt lgkmcnt(" #n ")" ::: "memory")
; #define PG8_BAR __builtin_amdgcn_s_barrier()
; #define PG8_SCHED __builtin_amdgcn_sched_barrier(0)
; template <class Epi, class Sched>
; __device__ __forceinline__ void gemm_phase(LAS unsigned char* lds, const Gemm g, const Sched& S, const Epi& E, const int wid) {
;     ...
;             PG8_LDA(At, 1, 1); PG8_STAGE(PG8_SB(1, 0), b3, voffB); PG8_STAGE(PG8_SB(1, 1), b3 + hstepB, voffB); PG8_STAGE(PG8_SA(1, 0), a3, voffA);
;             PG8_WAIT_V(8); PG8_WAIT_L(0); PG8_BAR; PG8_MMA(1, 0, At, B0); PG8_MMA(1, 1, At, B1); PG8_BAR; PG8_SCHED;
;         }
;         if (wr == 0) PG8_BAR;
;         E(acc, cur, wr, wc, fr, fq);
;         if (!has_next) break;
	s_add_i32 s60, s87, s65
	v_lshl_add_u64 v[168:169], v[168:169], 0, s[22:23]
	s_mov_b32 m0, s60
	ds_read_b128 v[216:219], v188 offset:49152
	ds_read_b128 v[220:223], v188 offset:50176
	ds_read_b128 v[224:227], v188 offset:51200
	ds_read_b128 v[228:231], v188 offset:52224
	ds_read_b128 v[232:235], v188 offset:53248
	ds_read_b128 v[236:239], v188 offset:54272
	ds_read_b128 v[240:243], v188 offset:55296
	ds_read_b128 v[244:247], v188 offset:56320
	global_load_lds_dwordx4 v[168:169], off
	s_add_i32 m0, s60, 0x2000
	s_add_u32 s58, s58, 0x40080
	v_lshl_add_u64 v[168:169], v[248:249], 0, s[22:23]
	s_addc_u32 s59, s59, 0
	s_add_i32 s60, s88, s65
	global_load_lds_dwordx4 v[168:169], off
	v_lshl_add_u64 v[168:169], s[58:59], 0, v[138:139]
	s_mov_b32 m0, s60
	s_nop 0
	global_load_lds_dwordx4 v[168:169], off
	v_lshl_add_u64 v[168:169], s[58:59], 0, v[142:143]
	s_add_i32 m0, s60, 0x2000
	s_nop 0
	global_load_lds_dwordx4 v[168:169], off
	v_lshl_add_u64 v[168:169], v[250:251], 0, s[22:23]
	s_mov_b32 m0, s70
	s_nop 0
	global_load_lds_dwordx4 v[168:169], off
	v_lshl_add_u64 v[168:169], v[252:253], 0, s[22:23]
	s_mov_b32 m0, s71
	s_nop 0
	global_load_lds_dwordx4 v[168:169], off
	s_waitcnt vmcnt(8)
	s_waitcnt lgkmcnt(0)
	s_barrier
	s_setprio 1
	s_waitcnt lgkmcnt(0)
	v_mfma_f32_16x16x32_bf16 v[60:63], v[128:131], v[216:219], v[60:63]
	v_mfma_f32_16x16x32_bf16 v[56:59], v[192:195], v[216:219], v[56:59]
	v_mfma_f32_16x16x32_bf16 v[44:47], v[128:131], v[224:227], v[44:47]
	v_mfma_f32_16x16x32_bf16 v[40:43], v[192:195], v[224:227], v[40:43]
	v_mfma_f32_16x16x32_bf16 v[28:31], v[128:131], v[232:235], v[28:31]
	v_mfma_f32_16x16x32_bf16 v[24:27], v[192:195], v[232:235], v[24:27]
	v_mfma_f32_16x16x32_bf16 v[12:15], v[128:131], v[240:243], v[12:15]
	v_mfma_f32_16x16x32_bf16 v[8:11], v[192:195], v[240:243], v[8:11]
	v_mfma_f32_16x16x32_bf16 v[60:63], v[132:135], v[220:223], v[60:63]
	v_mfma_f32_16x16x32_bf16 v[56:59], v[196:199], v[220:223], v[56:59]
	v_mfma_f32_16x16x32_bf16 v[44:47], v[132:135], v[228:231], v[44:47]
	v_mfma_f32_16x16x32_bf16 v[40:43], v[196:199], v[228:231], v[40:43]
	v_mfma_f32_16x16x32_bf16 v[28:31], v[132:135], v[236:239], v[28:31]
	v_mfma_f32_16x16x32_bf16 v[24:27], v[196:199], v[236:239], v[24:27]
	v_mfma_f32_16x16x32_bf16 v[12:15], v[132:135], v[244:247], v[12:15]
	v_mfma_f32_16x16x32_bf16 v[8:11], v[196:199], v[244:247], v[8:11]
	v_mfma_f32_16x16x32_bf16 v[52:55], v[200:203], v[216:219], v[52:55]
	v_mfma_f32_16x16x32_bf16 v[48:51], v[208:211], v[216:219], v[48:51]
	v_mfma_f32_16x16x32_bf16 v[36:39], v[200:203], v[224:227], v[36:39]
	v_mfma_f32_16x16x32_bf16 v[32:35], v[208:211], v[224:227], v[32:35]
	v_mfma_f32_16x16x32_bf16 v[20:23], v[200:203], v[232:235], v[20:23]
	v_mfma_f32_16x16x32_bf16 v[16:19], v[208:211], v[232:235], v[16:19]
	v_mfma_f32_16x16x32_bf16 v[4:7], v[200:203], v[240:243], v[4:7]
	v_mfma_f32_16x16x32_bf16 v[0:3], v[208:211], v[240:243], v[0:3]
	v_mfma_f32_16x16x32_bf16 v[52:55], v[204:207], v[220:223], v[52:55]
	v_mfma_f32_16x16x32_bf16 v[48:51], v[212:215], v[220:223], v[48:51]
	v_mfma_f32_16x16x32_bf16 v[36:39], v[204:207], v[228:231], v[36:39]
	v_mfma_f32_16x16x32_bf16 v[32:35], v[212:215], v[228:231], v[32:35]
	v_mfma_f32_16x16x32_bf16 v[20:23], v[204:207], v[236:239], v[20:23]
	v_mfma_f32_16x16x32_bf16 v[16:19], v[212:215], v[236:239], v[16:19]
	v_mfma_f32_16x16x32_bf16 v[4:7], v[204:207], v[244:247], v[4:7]
	v_mfma_f32_16x16x32_bf16 v[0:3], v[212:215], v[244:247], v[0:3]
	s_setprio 0
	s_barrier
	s_add_i32 s86, s86, 2
	s_add_u32 s56, s56, 0x100
	s_addc_u32 s57, s57, 0
	s_add_u32 s84, s84, 0x100
	s_addc_u32 s85, s85, 0
	s_cmp_gt_u32 s86, 13
	s_cbranch_scc0 .LBB0_247
	s_and_b64 vcc, exec, s[34:35]
	s_cbranch_vccnz .LBB0_252
	s_cmp_gt_i32 s54, 4
	s_mov_b64 s[56:57], -1
	s_cbranch_scc1 .LBB0_253

; #define PG8_STAGE(bufoff, gbase, voff) do { _Pragma("unroll") for (int _i = 0; _i < 2; ++_i) \
;         __builtin_amdgcn_global_load_lds((const unsigned*)((const char*)(gbase) + (voff)[_i]), (LAS unsigned*)(lds + (bufoff) + ldsw + _i * 8192), 16, 0, 0); } while (0)
; #define PG8_LDA(dst, b, h) do { _Pragma("unroll") for (int m = 0; m < 4; ++m) _Pragma("unroll") for (int k = 0; k < 2; ++k) dst[m][k] = *(const LAS bf16x8*)(lds + PG8_SA(b, h) + aoff + m * 2048 + k * 1024); } while (0)
; #define PG8_LDB(dst, b, h) do { _Pragma("unroll") for (int n = 0; n < 2; ++n) _Pragma("unroll") for (int k = 0; k < 2; ++k) dst[n][k] = *(const LAS bf16x8*)(lds + PG8_SB(b, h) + boff + n * 2048 + k * 1024); } while (0)
; #define PG8_MMA(ai, bj, At, Bt) do { __builtin_amdgcn_s_setprio(1); _Pragma("unroll") for (int m = 0; m < 4; ++m) _Pragma("unroll") for (int n = 0; n < 2; ++n) _Pragma("unroll") for (int k = 0; k < 2; ++k) \
;         acc[ai][bj][m][n] = __builtin_amdgcn_mfma_f32_16x16x32_bf16(Bt[n][k], At[m][k], acc[ai][bj][m][n], 0, 0, 0); __builtin_amdgcn_s_setprio(0); } while (0)
; #define PG8_WAIT_V(n) asm volatile("s_waitcnt vmcnt(" #n ")" ::: "memory")
; #define PG8_WAIT_L(n) asm volatile("s_waitcnt lgkmcnt(" #n ")" ::: "memory")
; #define PG8_BAR __builtin_amdgcn_s_barrier()
; #define PG8_SCHED __builtin_amdgcn_sched_barrier(0)
; template <class Epi, class Sched>
; __device__ __forceinline__ void gemm_phase(LAS unsigned char* lds, const Gemm g, const Sched& S, const Epi& E, const int wid) {
;     ...
;         for (int t = 0; t < nt; t += 2) {
;             const bool last = (t == nt - 2);
;             const char* a1 = cA + (size_t)(t + 1) * kstep;
;             const char* a2 = last ? nA : cA + (size_t)(t + 2) * kstep; const char* b2 = last ? nB : cB + (size_t)(t + 2) * kstep;
;             const char* a3 = a2 + kstep; const char* b3 = b2 + kstep;
;             PG8_LDB(B0, 0, 0); PG8_LDB(B1, 0, 1); PG8_SCHED; PG8_LDA(At, 0, 0); PG8_STAGE(PG8_SA(1, 1), a1 + hstepA, voffA);
;             PG8_WAIT_V(8); PG8_WAIT_L(0); PG8_BAR; PG8_MMA(0, 0, At, B0); PG8_MMA(0, 1, At, B1); PG8_BAR; PG8_SCHED;
;             PG8_LDA(At, 0, 1); PG8_STAGE(PG8_SB(0, 0), b2, voffB); PG8_STAGE(PG8_SB(0, 1), b2 + hstepB, voffB); PG8_STAGE(PG8_SA(0, 0), a2, voffA);
;             PG8_WAIT_V(8); PG8_WAIT_L(0); PG8_BAR; PG8_MMA(1, 0, At, B0); PG8_MMA(1, 1, At, B1); PG8_BAR; PG8_SCHED;
.LBB0_459:
	ds_read_b128 v[72:75], v199
	ds_read_b128 v[80:83], v199 offset:1024
	ds_read_b128 v[84:87], v199 offset:2048
	ds_read_b128 v[92:95], v199 offset:3072
	ds_read_b128 v[144:147], v200
	ds_read_b128 v[148:151], v200 offset:1024
	ds_read_b128 v[152:155], v200 offset:2048
	ds_read_b128 v[156:159], v200 offset:3072
	s_add_u32 s56, s54, 0xfffc0080
	s_addc_u32 s57, s55, -1
	s_cmp_eq_u32 s88, 12
	s_cselect_b32 s59, s45, s57
	s_cselect_b32 s58, s51, s56
	s_cselect_b32 s57, s43, s87
	s_cselect_b32 s56, s85, s86
	v_lshl_add_u64 v[210:211], s[54:55], 0, v[164:165]
	s_add_i32 m0, s53, 0xc000
	ds_read_b128 v[172:175], v201
	ds_read_b128 v[176:179], v201 offset:1024
	ds_read_b128 v[180:183], v201 offset:2048
	ds_read_b128 v[184:187], v201 offset:3072
	ds_read_b128 v[188:191], v201 offset:4096
	ds_read_b128 v[192:195], v201 offset:5120
	ds_read_b128 v[202:205], v201 offset:6144
	ds_read_b128 v[206:209], v201 offset:7168
	global_load_lds_dwordx4 v[210:211], off
	v_lshl_add_u64 v[210:211], s[54:55], 0, v[166:167]
	s_add_i32 m0, s53, 0xe000
	s_nop 0
	global_load_lds_dwordx4 v[210:211], off
	s_waitcnt vmcnt(8)
	s_waitcnt lgkmcnt(0)
	s_barrier
	s_setprio 1
	s_waitcnt lgkmcnt(0)
	v_mfma_f32_16x16x32_bf16 v[140:143], v[72:75], v[172:175], v[140:143]
	v_mfma_f32_16x16x32_bf16 v[136:139], v[84:87], v[172:175], v[136:139]
	v_mfma_f32_16x16x32_bf16 v[124:127], v[72:75], v[180:183], v[124:127]
	v_mfma_f32_16x16x32_bf16 v[120:123], v[84:87], v[180:183], v[120:123]
	v_mfma_f32_16x16x32_bf16 v[108:111], v[72:75], v[188:191], v[108:111]
	v_mfma_f32_16x16x32_bf16 v[104:107], v[84:87], v[188:191], v[104:107]
	v_mfma_f32_16x16x32_bf16 v[88:91], v[72:75], v[202:205], v[88:91]
	v_mfma_f32_16x16x32_bf16 v[76:79], v[84:87], v[202:205], v[76:79]
	v_mfma_f32_16x16x32_bf16 v[140:143], v[80:83], v[176:179], v[140:143]
	v_mfma_f32_16x16x32_bf16 v[136:139], v[92:95], v[176:179], v[136:139]
	v_mfma_f32_16x16x32_bf16 v[124:127], v[80:83], v[184:187], v[124:127]
	v_mfma_f32_16x16x32_bf16 v[120:123], v[92:95], v[184:187], v[120:123]
	v_mfma_f32_16x16x32_bf16 v[108:111], v[80:83], v[192:195], v[108:111]
	v_mfma_f32_16x16x32_bf16 v[104:107], v[92:95], v[192:195], v[104:107]
	v_mfma_f32_16x16x32_bf16 v[88:91], v[80:83], v[206:209], v[88:91]
	v_mfma_f32_16x16x32_bf16 v[76:79], v[92:95], v[206:209], v[76:79]
	v_mfma_f32_16x16x32_bf16 v[132:135], v[144:147], v[172:175], v[132:135]
	v_mfma_f32_16x16x32_bf16 v[128:131], v[152:155], v[172:175], v[128:131]
	v_mfma_f32_16x16x32_bf16 v[116:119], v[144:147], v[180:183], v[116:119]
	v_mfma_f32_16x16x32_bf16 v[112:115], v[152:155], v[180:183], v[112:115]
	v_mfma_f32_16x16x32_bf16 v[100:103], v[144:147], v[188:191], v[100:103]
	v_mfma_f32_16x16x32_bf16 v[96:99], v[152:155], v[188:191], v[96:99]
	v_mfma_f32_16x16x32_bf16 v[68:71], v[144:147], v[202:205], v[68:71]
	v_mfma_f32_16x16x32_bf16 v[64:67], v[152:155], v[202:205], v[64:67]
	v_mfma_f32_16x16x32_bf16 v[132:135], v[148:151], v[176:179], v[132:135]
	v_mfma_f32_16x16x32_bf16 v[128:131], v[156:159], v[176:179], v[128:131]
	v_mfma_f32_16x16x32_bf16 v[116:119], v[148:151], v[184:187], v[116:119]
	v_mfma_f32_16x16x32_bf16 v[112:115], v[156:159], v[184:187], v[112:115]
	v_mfma_f32_16x16x32_bf16 v[100:103], v[148:151], v[192:195], v[100:103]
	v_mfma_f32_16x16x32_bf16 v[96:99], v[156:159], v[192:195], v[96:99]
	v_mfma_f32_16x16x32_bf16 v[68:71], v[148:151], v[206:209], v[68:71]
	v_mfma_f32_16x16x32_bf16 v[64:67], v[156:159], v[206:209], v[64:67]
	s_setprio 0
	s_barrier
	s_add_i32 s89, s78, s63
	v_lshl_add_u64 v[210:211], s[56:57], 0, v[160:161]
	s_mov_b32 m0, s89
	ds_read_b128 v[172:175], v201 offset:16384
	ds_read_b128 v[176:179], v201 offset:17408
	ds_read_b128 v[180:183], v201 offset:18432
	ds_read_b128 v[184:187], v201 offset:19456
	ds_read_b128 v[188:191], v201 offset:20480
	ds_read_b128 v[192:195], v201 offset:21504
	ds_read_b128 v[202:205], v201 offset:22528
	ds_read_b128 v[206:209], v201 offset:23552
	global_load_lds_dwordx4 v[210:211], off
	s_add_i32 m0, s89, 0x2000
	s_add_u32 s90, s56, 0x40000
	v_lshl_add_u64 v[212:213], s[56:57], 0, v[162:163]
	s_addc_u32 s91, s57, 0
	s_add_i32 s89, s79, s63
	global_load_lds_dwordx4 v[212:213], off
	v_lshl_add_u64 v[214:215], s[90:91], 0, v[160:161]
	s_mov_b32 m0, s89
	v_lshl_add_u64 v[216:217], s[58:59], 0, v[162:163]
	global_load_lds_dwordx4 v[214:215], off
	v_lshl_add_u64 v[214:215], s[90:91], 0, v[162:163]
	s_add_i32 m0, s89, 0x2000
	s_nop 0
	global_load_lds_dwordx4 v[214:215], off
	v_lshl_add_u64 v[214:215], s[58:59], 0, v[160:161]
	s_mov_b32 m0, s53
	s_nop 0
	global_load_lds_dwordx4 v[214:215], off
	s_mov_b32 m0, s64
	s_nop 0
	global_load_lds_dwordx4 v[216:217], off
	s_waitcnt vmcnt(8)
	s_waitcnt lgkmcnt(0)
	s_barrier
; #define PG8_STAGE(bufoff, gbase, voff) do { _Pragma("unroll") for (int _i = 0; _i < 2; ++_i) \
;         __builtin_amdgcn_global_load_lds((const unsigned*)((const char*)(gbase) + (voff)[_i]), (LAS unsigned*)(lds + (bufoff) + ldsw + _i * 8192), 16, 0, 0); } while (0)
; #define PG8_LDA(dst, b, h) do { _Pragma("unroll") for (int m = 0; m < 4; ++m) _Pragma("unroll") for (int k = 0; k < 2; ++k) dst[m][k] = *(const LAS bf16x8*)(lds + PG8_SA(b, h) + aoff + m * 2048 + k * 1024); } while (0)
; #define PG8_LDB(dst, b, h) do { _Pragma("unroll") for (int n = 0; n < 2; ++n) _Pragma("unroll") for (int k = 0; k < 2; ++k) dst[n][k] = *(const LAS bf16x8*)(lds + PG8_SB(b, h) + boff + n * 2048 + k * 1024); } while (0)
; #define PG8_MMA(ai, bj, At, Bt) do { __builtin_amdgcn_s_setprio(1); _Pragma("unroll") for (int m = 0; m < 4; ++m) _Pragma("unroll") for (int n = 0; n < 2; ++n) _Pragma("unroll") for (int k = 0; k < 2; ++k) \
;         acc[ai][bj][m][n] = __builtin_amdgcn_mfma_f32_16x16x32_bf16(Bt[n][k], At[m][k], acc[ai][bj][m][n], 0, 0, 0); __builtin_amdgcn_s_setprio(0); } while (0)
; #define PG8_WAIT_V(n) asm volatile("s_waitcnt vmcnt(" #n ")" ::: "memory")
; #define PG8_WAIT_L(n) asm volatile("s_waitcnt lgkmcnt(" #n ")" ::: "memory")
; #define PG8_BAR __builtin_amdgcn_s_barrier()
; #define PG8_SCHED __builtin_amdgcn_sched_barrier(0)
; template <class Epi, class Sched>
; __device__ __forceinline__ void gemm_phase(LAS unsigned char* lds, const Gemm g, const Sched& S, const Epi& E, const int wid) {
;     ...
;             PG8_WAIT_V(8); PG8_WAIT_L(0); PG8_BAR; PG8_MMA(1, 0, At, B0); PG8_MMA(1, 1, At, B1); PG8_BAR; PG8_SCHED;
;             PG8_LDB(B0, 1, 0); PG8_LDB(B1, 1, 1); PG8_SCHED; PG8_LDA(At, 1, 0); PG8_STAGE(PG8_SA(0, 1), a2 + hstepA, voffA);
;             PG8_WAIT_V(8); PG8_WAIT_L(0); PG8_BAR; PG8_MMA(0, 0, At, B0); PG8_MMA(0, 1, At, B1); PG8_BAR; PG8_SCHED;
	s_setprio 1
	s_waitcnt lgkmcnt(0)
	v_mfma_f32_16x16x32_bf16 v[60:63], v[72:75], v[172:175], v[60:63]
	v_mfma_f32_16x16x32_bf16 v[56:59], v[84:87], v[172:175], v[56:59]
	v_mfma_f32_16x16x32_bf16 v[44:47], v[72:75], v[180:183], v[44:47]
	v_mfma_f32_16x16x32_bf16 v[40:43], v[84:87], v[180:183], v[40:43]
	v_mfma_f32_16x16x32_bf16 v[28:31], v[72:75], v[188:191], v[28:31]
	v_mfma_f32_16x16x32_bf16 v[24:27], v[84:87], v[188:191], v[24:27]
	v_mfma_f32_16x16x32_bf16 v[12:15], v[72:75], v[202:205], v[12:15]
	v_mfma_f32_16x16x32_bf16 v[8:11], v[84:87], v[202:205], v[8:11]
	v_mfma_f32_16x16x32_bf16 v[60:63], v[80:83], v[176:179], v[60:63]
	v_mfma_f32_16x16x32_bf16 v[56:59], v[92:95], v[176:179], v[56:59]
	v_mfma_f32_16x16x32_bf16 v[44:47], v[80:83], v[184:187], v[44:47]
	v_mfma_f32_16x16x32_bf16 v[40:43], v[92:95], v[184:187], v[40:43]
	v_mfma_f32_16x16x32_bf16 v[28:31], v[80:83], v[192:195], v[28:31]
	v_mfma_f32_16x16x32_bf16 v[24:27], v[92:95], v[192:195], v[24:27]
	v_mfma_f32_16x16x32_bf16 v[12:15], v[80:83], v[206:209], v[12:15]
	v_mfma_f32_16x16x32_bf16 v[8:11], v[92:95], v[206:209], v[8:11]
	v_mfma_f32_16x16x32_bf16 v[52:55], v[144:147], v[172:175], v[52:55]
	v_mfma_f32_16x16x32_bf16 v[48:51], v[152:155], v[172:175], v[48:51]
	v_mfma_f32_16x16x32_bf16 v[36:39], v[144:147], v[180:183], v[36:39]
	v_mfma_f32_16x16x32_bf16 v[32:35], v[152:155], v[180:183], v[32:35]
	v_mfma_f32_16x16x32_bf16 v[20:23], v[144:147], v[188:191], v[20:23]
	v_mfma_f32_16x16x32_bf16 v[16:19], v[152:155], v[188:191], v[16:19]
	v_mfma_f32_16x16x32_bf16 v[4:7], v[144:147], v[202:205], v[4:7]
	v_mfma_f32_16x16x32_bf16 v[0:3], v[152:155], v[202:205], v[0:3]
	v_mfma_f32_16x16x32_bf16 v[52:55], v[148:151], v[176:179], v[52:55]
	v_mfma_f32_16x16x32_bf16 v[48:51], v[156:159], v[176:179], v[48:51]
	v_mfma_f32_16x16x32_bf16 v[36:39], v[148:151], v[184:187], v[36:39]
	v_mfma_f32_16x16x32_bf16 v[32:35], v[156:159], v[184:187], v[32:35]
	v_mfma_f32_16x16x32_bf16 v[20:23], v[148:151], v[192:195], v[20:23]
	v_mfma_f32_16x16x32_bf16 v[16:19], v[156:159], v[192:195], v[16:19]
	v_mfma_f32_16x16x32_bf16 v[4:7], v[148:151], v[206:209], v[4:7]
	v_mfma_f32_16x16x32_bf16 v[0:3], v[156:159], v[206:209], v[0:3]
	s_setprio 0
	s_barrier
	s_add_i32 s89, 0, 0x18000
	s_add_i32 s90, 0, 0x1c000
	v_add_u32_e32 v92, s89, v197
	v_add_u32_e32 v156, s90, v197
	ds_read_b128 v[72:75], v92
	ds_read_b128 v[80:83], v92 offset:1024
	ds_read_b128 v[84:87], v92 offset:2048
	ds_read_b128 v[92:95], v92 offset:3072
	ds_read_b128 v[144:147], v156
	ds_read_b128 v[148:151], v156 offset:1024
	ds_read_b128 v[152:155], v156 offset:2048
	ds_read_b128 v[156:159], v156 offset:3072
	s_add_u32 s58, s58, 0x40000
	s_addc_u32 s59, s59, 0
	s_mov_b32 m0, s65
	v_lshl_add_u64 v[218:219], s[58:59], 0, v[160:161]
	ds_read_b128 v[172:175], v201 offset:32768
	ds_read_b128 v[176:179], v201 offset:33792
	ds_read_b128 v[180:183], v201 offset:34816
	ds_read_b128 v[184:187], v201 offset:35840
	ds_read_b128 v[188:191], v201 offset:36864
	ds_read_b128 v[192:195], v201 offset:37888
	ds_read_b128 v[202:205], v201 offset:38912
	ds_read_b128 v[206:209], v201 offset:39936
	global_load_lds_dwordx4 v[218:219], off
	v_lshl_add_u64 v[218:219], s[58:59], 0, v[162:163]
	s_mov_b32 m0, s66
	s_nop 0
	global_load_lds_dwordx4 v[218:219], off
	s_waitcnt vmcnt(8)
	s_waitcnt lgkmcnt(0)
	s_barrier
	s_setprio 1
	s_waitcnt lgkmcnt(0)
	v_mfma_f32_16x16x32_bf16 v[140:143], v[72:75], v[172:175], v[140:143]
	v_mfma_f32_16x16x32_bf16 v[136:139], v[84:87], v[172:175], v[136:139]
	v_mfma_f32_16x16x32_bf16 v[124:127], v[72:75], v[180:183], v[124:127]
	v_mfma_f32_16x16x32_bf16 v[120:123], v[84:87], v[180:183], v[120:123]
	v_mfma_f32_16x16x32_bf16 v[108:111], v[72:75], v[188:191], v[108:111]
	v_mfma_f32_16x16x32_bf16 v[104:107], v[84:87], v[188:191], v[104:107]
	v_mfma_f32_16x16x32_bf16 v[88:91], v[72:75], v[202:205], v[88:91]
	v_mfma_f32_16x16x32_bf16 v[76:79], v[84:87], v[202:205], v[76:79]
	v_mfma_f32_16x16x32_bf16 v[140:143], v[80:83], v[176:179], v[140:143]
	v_mfma_f32_16x16x32_bf16 v[136:139], v[92:95], v[176:179], v[136:139]
	v_mfma_f32_16x16x32_bf16 v[124:127], v[80:83], v[184:187], v[124:127]
	v_mfma_f32_16x16x32_bf16 v[120:123], v[92:95], v[184:187], v[120:123]
	v_mfma_f32_16x16x32_bf16 v[108:111], v[80:83], v[192:195], v[108:111]
	v_mfma_f32_16x16x32_bf16 v[104:107], v[92:95], v[192:195], v[104:107]
	v_mfma_f32_16x16x32_bf16 v[88:91], v[80:83], v[206:209], v[88:91]
	v_mfma_f32_16x16x32_bf16 v[76:79], v[92:95], v[206:209], v[76:79]
	v_mfma_f32_16x16x32_bf16 v[132:135], v[144:147], v[172:175], v[132:135]
	v_mfma_f32_16x16x32_bf16 v[128:131], v[152:155], v[172:175], v[128:131]
	v_mfma_f32_16x16x32_bf16 v[116:119], v[144:147], v[180:183], v[116:119]
	v_mfma_f32_16x16x32_bf16 v[112:115], v[152:155], v[180:183], v[112:115]
	v_mfma_f32_16x16x32_bf16 v[100:103], v[144:147], v[188:191], v[100:103]
	v_mfma_f32_16x16x32_bf16 v[96:99], v[152:155], v[188:191], v[96:99]
	v_mfma_f32_16x16x32_bf16 v[68:71], v[144:147], v[202:205], v[68:71]
	v_mfma_f32_16x16x32_bf16 v[64:67], v[152:155], v[202:205], v[64:67]
	v_mfma_f32_16x16x32_bf16 v[132:135], v[148:151], v[176:179], v[132:135]
	v_mfma_f32_16x16x32_bf16 v[128:131], v[156:159], v[176:179], v[128:131]
	v_mfma_f32_16x16x32_bf16 v[116:119], v[148:151], v[184:187], v[116:119]
	v_mfma_f32_16x16x32_bf16 v[112:115], v[156:159], v[184:187], v[112:115]
	v_mfma_f32_16x16x32_bf16 v[100:103], v[148:151], v[192:195], v[100:103]
	v_mfma_f32_16x16x32_bf16 v[96:99], v[156:159], v[192:195], v[96:99]
	v_mfma_f32_16x16x32_bf16 v[68:71], v[148:151], v[206:209], v[68:71]
	v_mfma_f32_16x16x32_bf16 v[64:67], v[156:159], v[206:209], v[64:67]
	s_setprio 0
	s_barrier
; #define PG8_STAGE(bufoff, gbase, voff) do { _Pragma("unroll") for (int _i = 0; _i < 2; ++_i) \
;         __builtin_amdgcn_global_load_lds((const unsigned*)((const char*)(gbase) + (voff)[_i]), (LAS unsigned*)(lds + (bufoff) + ldsw + _i * 8192), 16, 0, 0); } while (0)
; #define PG8_LDA(dst, b, h) do { _Pragma("unroll") for (int m = 0; m < 4; ++m) _Pragma("unroll") for (int k = 0; k < 2; ++k) dst[m][k] = *(const LAS bf16x8*)(lds + PG8_SA(b, h) + aoff + m * 2048 + k * 1024); } while (0)
; #define PG8_MMA(ai, bj, At, Bt) do { __builtin_amdgcn_s_setprio(1); _Pragma("unroll") for (int m = 0; m < 4; ++m) _Pragma("unroll") for (int n = 0; n < 2; ++n) _Pragma("unroll") for (int k = 0; k < 2; ++k) \
;         acc[ai][bj][m][n] = __builtin_amdgcn_mfma_f32_16x16x32_bf16(Bt[n][k], At[m][k], acc[ai][bj][m][n], 0, 0, 0); __builtin_amdgcn_s_setprio(0); } while (0)
; #define PG8_WAIT_V(n) asm volatile("s_waitcnt vmcnt(" #n ")" ::: "memory")
; #define PG8_WAIT_L(n) asm volatile("s_waitcnt lgkmcnt(" #n ")" ::: "memory")
; #define PG8_BAR __builtin_amdgcn_s_barrier()
; #define PG8_SCHED __builtin_amdgcn_sched_barrier(0)
; template <class Epi, class Sched>
; __device__ __forceinline__ void gemm_phase(LAS unsigned char* lds, const Gemm g, const Sched& S, const Epi& E, const int wid) {
;     ...
;             PG8_LDA(At, 1, 1); PG8_STAGE(PG8_SB(1, 0), b3, voffB); PG8_STAGE(PG8_SB(1, 1), b3 + hstepB, voffB); PG8_STAGE(PG8_SA(1, 0), a3, voffA);
;             PG8_WAIT_V(8); PG8_WAIT_L(0); PG8_BAR; PG8_MMA(1, 0, At, B0); PG8_MMA(1, 1, At, B1); PG8_BAR; PG8_SCHED;
;         }
;         if (wr == 0) PG8_BAR;
;         E(acc, cur, wr, wc, fr, fq);
;         if (!has_next) break;
	s_add_i32 s58, s89, s63
	v_lshl_add_u64 v[210:211], v[210:211], 0, s[34:35]
	s_mov_b32 m0, s58
	ds_read_b128 v[172:175], v201 offset:49152
	ds_read_b128 v[176:179], v201 offset:50176
	ds_read_b128 v[180:183], v201 offset:51200
	ds_read_b128 v[184:187], v201 offset:52224
	ds_read_b128 v[188:191], v201 offset:53248
	ds_read_b128 v[192:195], v201 offset:54272
	ds_read_b128 v[202:205], v201 offset:55296
	ds_read_b128 v[206:209], v201 offset:56320
	global_load_lds_dwordx4 v[210:211], off
	s_add_i32 m0, s58, 0x2000
	s_add_u32 s56, s56, 0x40080
	v_lshl_add_u64 v[210:211], v[212:213], 0, s[34:35]
	s_addc_u32 s57, s57, 0
	s_add_i32 s58, s90, s63
	global_load_lds_dwordx4 v[210:211], off
	v_lshl_add_u64 v[210:211], s[56:57], 0, v[160:161]
	s_mov_b32 m0, s58
	s_nop 0
	global_load_lds_dwordx4 v[210:211], off
	v_lshl_add_u64 v[210:211], s[56:57], 0, v[162:163]
	s_add_i32 m0, s58, 0x2000
	s_nop 0
	global_load_lds_dwordx4 v[210:211], off
	v_lshl_add_u64 v[210:211], v[214:215], 0, s[34:35]
	s_mov_b32 m0, s72
	s_nop 0
	global_load_lds_dwordx4 v[210:211], off
	v_lshl_add_u64 v[210:211], v[216:217], 0, s[34:35]
	s_mov_b32 m0, s73
	s_nop 0
	global_load_lds_dwordx4 v[210:211], off
	s_waitcnt vmcnt(8)
	s_waitcnt lgkmcnt(0)
	s_barrier
	s_setprio 1
	s_waitcnt lgkmcnt(0)
	v_mfma_f32_16x16x32_bf16 v[60:63], v[72:75], v[172:175], v[60:63]
	v_mfma_f32_16x16x32_bf16 v[56:59], v[84:87], v[172:175], v[56:59]
	v_mfma_f32_16x16x32_bf16 v[44:47], v[72:75], v[180:183], v[44:47]
	v_mfma_f32_16x16x32_bf16 v[40:43], v[84:87], v[180:183], v[40:43]
	v_mfma_f32_16x16x32_bf16 v[28:31], v[72:75], v[188:191], v[28:31]
	v_mfma_f32_16x16x32_bf16 v[24:27], v[84:87], v[188:191], v[24:27]
	v_mfma_f32_16x16x32_bf16 v[12:15], v[72:75], v[202:205], v[12:15]
	v_mfma_f32_16x16x32_bf16 v[8:11], v[84:87], v[202:205], v[8:11]
	v_mfma_f32_16x16x32_bf16 v[60:63], v[80:83], v[176:179], v[60:63]
	v_mfma_f32_16x16x32_bf16 v[56:59], v[92:95], v[176:179], v[56:59]
	v_mfma_f32_16x16x32_bf16 v[44:47], v[80:83], v[184:187], v[44:47]
	v_mfma_f32_16x16x32_bf16 v[40:43], v[92:95], v[184:187], v[40:43]
	v_mfma_f32_16x16x32_bf16 v[28:31], v[80:83], v[192:195], v[28:31]
	v_mfma_f32_16x16x32_bf16 v[24:27], v[92:95], v[192:195], v[24:27]
	v_mfma_f32_16x16x32_bf16 v[12:15], v[80:83], v[206:209], v[12:15]
	v_mfma_f32_16x16x32_bf16 v[8:11], v[92:95], v[206:209], v[8:11]
	v_mfma_f32_16x16x32_bf16 v[52:55], v[144:147], v[172:175], v[52:55]
	v_mfma_f32_16x16x32_bf16 v[48:51], v[152:155], v[172:175], v[48:51]
	v_mfma_f32_16x16x32_bf16 v[36:39], v[144:147], v[180:183], v[36:39]
	v_mfma_f32_16x16x32_bf16 v[32:35], v[152:155], v[180:183], v[32:35]
	v_mfma_f32_16x16x32_bf16 v[20:23], v[144:147], v[188:191], v[20:23]
	v_mfma_f32_16x16x32_bf16 v[16:19], v[152:155], v[188:191], v[16:19]
	v_mfma_f32_16x16x32_bf16 v[4:7], v[144:147], v[202:205], v[4:7]
	v_mfma_f32_16x16x32_bf16 v[0:3], v[152:155], v[202:205], v[0:3]
	v_mfma_f32_16x16x32_bf16 v[52:55], v[148:151], v[176:179], v[52:55]
	v_mfma_f32_16x16x32_bf16 v[48:51], v[156:159], v[176:179], v[48:51]
	v_mfma_f32_16x16x32_bf16 v[36:39], v[148:151], v[184:187], v[36:39]
	v_mfma_f32_16x16x32_bf16 v[32:35], v[156:159], v[184:187], v[32:35]
	v_mfma_f32_16x16x32_bf16 v[20:23], v[148:151], v[192:195], v[20:23]
	v_mfma_f32_16x16x32_bf16 v[16:19], v[156:159], v[192:195], v[16:19]
	v_mfma_f32_16x16x32_bf16 v[4:7], v[148:151], v[206:209], v[4:7]
	v_mfma_f32_16x16x32_bf16 v[0:3], v[156:159], v[206:209], v[0:3]
	s_setprio 0
	s_barrier
	s_add_i32 s88, s88, 2
	s_add_u32 s54, s54, 0x100
	s_addc_u32 s55, s55, 0
	s_add_u32 s86, s86, 0x100
	s_addc_u32 s87, s87, 0
	s_cmp_gt_u32 s88, 13
	s_cbranch_scc0 .LBB0_459
	s_and_b64 vcc, exec, s[38:39]
	s_cbranch_vccz .LBB0_462
	s_barrier

; #define PG8_STAGE(bufoff, gbase, voff) do { _Pragma("unroll") for (int _i = 0; _i < 2; ++_i) \
;         __builtin_amdgcn_global_load_lds((const unsigned*)((const char*)(gbase) + (voff)[_i]), (LAS unsigned*)(lds + (bufoff) + ldsw + _i * 8192), 16, 0, 0); } while (0)
; #define PG8_LDA(dst, b, h) do { _Pragma("unroll") for (int m = 0; m < 4; ++m) _Pragma("unroll") for (int k = 0; k < 2; ++k) dst[m][k] = *(const LAS bf16x8*)(lds + PG8_SA(b, h) + aoff + m * 2048 + k * 1024); } while (0)
; #define PG8_LDB(dst, b, h) do { _Pragma("unroll") for (int n = 0; n < 2; ++n) _Pragma("unroll") for (int k = 0; k < 2; ++k) dst[n][k] = *(const LAS bf16x8*)(lds + PG8_SB(b, h) + boff + n * 2048 + k * 1024); } while (0)
; #define PG8_MMA(ai, bj, At, Bt) do { __builtin_amdgcn_s_setprio(1); _Pragma("unroll") for (int m = 0; m < 4; ++m) _Pragma("unroll") for (int n = 0; n < 2; ++n) _Pragma("unroll") for (int k = 0; k < 2; ++k) \
;         acc[ai][bj][m][n] = __builtin_amdgcn_mfma_f32_16x16x32_bf16(Bt[n][k], At[m][k], acc[ai][bj][m][n], 0, 0, 0); __builtin_amdgcn_s_setprio(0); } while (0)
; #define PG8_WAIT_V(n) asm volatile("s_waitcnt vmcnt(" #n ")" ::: "memory")
; #define PG8_WAIT_L(n) asm volatile("s_waitcnt lgkmcnt(" #n ")" ::: "memory")
; #define PG8_BAR __builtin_amdgcn_s_barrier()
; #define PG8_SCHED __builtin_amdgcn_sched_barrier(0)
; template <class Epi, class Sched>
; __device__ __forceinline__ void gemm_phase(LAS unsigned char* lds, const Gemm g, const Sched& S, const Epi& E, const int wid) {
;     ...
;         for (int t = 0; t < nt; t += 2) {
;             const bool last = (t == nt - 2);
;             const char* a1 = cA + (size_t)(t + 1) * kstep;
;             const char* a2 = last ? nA : cA + (size_t)(t + 2) * kstep; const char* b2 = last ? nB : cB + (size_t)(t + 2) * kstep;
;             const char* a3 = a2 + kstep; const char* b3 = b2 + kstep;
;             PG8_LDB(B0, 0, 0); PG8_LDB(B1, 0, 1); PG8_SCHED; PG8_LDA(At, 0, 0); PG8_STAGE(PG8_SA(1, 1), a1 + hstepA, voffA);
;             PG8_WAIT_V(8); PG8_WAIT_L(0); PG8_BAR; PG8_MMA(0, 0, At, B0); PG8_MMA(0, 1, At, B1); PG8_BAR; PG8_SCHED;
;             PG8_LDA(At, 0, 1); PG8_STAGE(PG8_SB(0, 0), b2, voffB); PG8_STAGE(PG8_SB(0, 1), b2 + hstepB, voffB); PG8_STAGE(PG8_SA(0, 0), a2, voffA);
;             PG8_WAIT_V(8); PG8_WAIT_L(0); PG8_BAR; PG8_MMA(1, 0, At, B0); PG8_MMA(1, 1, At, B1); PG8_BAR; PG8_SCHED;
.LBB0_546:
	ds_read_b128 v[128:131], v167
	ds_read_b128 v[132:135], v167 offset:1024
	ds_read_b128 v[136:139], v167 offset:2048
	ds_read_b128 v[140:143], v167 offset:3072
	ds_read_b128 v[172:175], v168
	ds_read_b128 v[176:179], v168 offset:1024
	ds_read_b128 v[180:183], v168 offset:2048
	ds_read_b128 v[184:187], v168 offset:3072
	s_add_u32 s48, s46, 0xfffc0080
	s_addc_u32 s49, s47, -1
	s_cmp_eq_u32 s81, 12
	s_cselect_b32 s51, s39, s49
	s_cselect_b32 s50, s77, s48
	s_cselect_b32 s49, s37, s80
	s_cselect_b32 s48, s78, s79
	v_lshl_add_u64 v[164:165], s[46:47], 0, v[156:157]
	s_add_i32 m0, s57, 0xc000
	ds_read_b128 v[188:191], v169
	ds_read_b128 v[192:195], v169 offset:1024
	ds_read_b128 v[196:199], v169 offset:2048
	ds_read_b128 v[200:203], v169 offset:3072
	ds_read_b128 v[204:207], v169 offset:4096
	ds_read_b128 v[208:211], v169 offset:5120
	ds_read_b128 v[212:215], v169 offset:6144
	ds_read_b128 v[216:219], v169 offset:7168
	global_load_lds_dwordx4 v[164:165], off
	v_lshl_add_u64 v[164:165], s[46:47], 0, v[158:159]
	s_add_i32 m0, s57, 0xe000
	s_nop 0
	global_load_lds_dwordx4 v[164:165], off
	s_waitcnt vmcnt(8)
	s_waitcnt lgkmcnt(0)
	s_barrier
	s_setprio 1
	s_waitcnt lgkmcnt(0)
	v_mfma_f32_16x16x32_bf16 v[124:127], v[128:131], v[188:191], v[124:127]
	v_mfma_f32_16x16x32_bf16 v[120:123], v[136:139], v[188:191], v[120:123]
	v_mfma_f32_16x16x32_bf16 v[116:119], v[128:131], v[196:199], v[116:119]
	v_mfma_f32_16x16x32_bf16 v[112:115], v[136:139], v[196:199], v[112:115]
	v_mfma_f32_16x16x32_bf16 v[108:111], v[128:131], v[204:207], v[108:111]
	v_mfma_f32_16x16x32_bf16 v[96:99], v[136:139], v[204:207], v[96:99]
	v_mfma_f32_16x16x32_bf16 v[80:83], v[128:131], v[212:215], v[80:83]
	v_mfma_f32_16x16x32_bf16 v[72:75], v[136:139], v[212:215], v[72:75]
	v_mfma_f32_16x16x32_bf16 v[124:127], v[132:135], v[192:195], v[124:127]
	v_mfma_f32_16x16x32_bf16 v[120:123], v[140:143], v[192:195], v[120:123]
	v_mfma_f32_16x16x32_bf16 v[116:119], v[132:135], v[200:203], v[116:119]
	v_mfma_f32_16x16x32_bf16 v[112:115], v[140:143], v[200:203], v[112:115]
	v_mfma_f32_16x16x32_bf16 v[108:111], v[132:135], v[208:211], v[108:111]
	v_mfma_f32_16x16x32_bf16 v[96:99], v[140:143], v[208:211], v[96:99]
	v_mfma_f32_16x16x32_bf16 v[80:83], v[132:135], v[216:219], v[80:83]
	v_mfma_f32_16x16x32_bf16 v[72:75], v[140:143], v[216:219], v[72:75]
	v_mfma_f32_16x16x32_bf16 v[104:107], v[172:175], v[188:191], v[104:107]
	v_mfma_f32_16x16x32_bf16 v[100:103], v[180:183], v[188:191], v[100:103]
	v_mfma_f32_16x16x32_bf16 v[92:95], v[172:175], v[196:199], v[92:95]
	v_mfma_f32_16x16x32_bf16 v[88:91], v[180:183], v[196:199], v[88:91]
	v_mfma_f32_16x16x32_bf16 v[84:87], v[172:175], v[204:207], v[84:87]
	v_mfma_f32_16x16x32_bf16 v[76:79], v[180:183], v[204:207], v[76:79]
	v_mfma_f32_16x16x32_bf16 v[68:71], v[172:175], v[212:215], v[68:71]
	v_mfma_f32_16x16x32_bf16 v[64:67], v[180:183], v[212:215], v[64:67]
	v_mfma_f32_16x16x32_bf16 v[104:107], v[176:179], v[192:195], v[104:107]
	v_mfma_f32_16x16x32_bf16 v[100:103], v[184:187], v[192:195], v[100:103]
	v_mfma_f32_16x16x32_bf16 v[92:95], v[176:179], v[200:203], v[92:95]
	v_mfma_f32_16x16x32_bf16 v[88:91], v[184:187], v[200:203], v[88:91]
	v_mfma_f32_16x16x32_bf16 v[84:87], v[176:179], v[208:211], v[84:87]
	v_mfma_f32_16x16x32_bf16 v[76:79], v[184:187], v[208:211], v[76:79]
	v_mfma_f32_16x16x32_bf16 v[68:71], v[176:179], v[216:219], v[68:71]
	v_mfma_f32_16x16x32_bf16 v[64:67], v[184:187], v[216:219], v[64:67]
	s_setprio 0
	s_barrier
	s_add_i32 s82, s70, s54
	v_lshl_add_u64 v[164:165], s[48:49], 0, v[148:149]
	s_mov_b32 m0, s82
	ds_read_b128 v[188:191], v169 offset:16384
	ds_read_b128 v[192:195], v169 offset:17408
	ds_read_b128 v[196:199], v169 offset:18432
	ds_read_b128 v[200:203], v169 offset:19456
	ds_read_b128 v[204:207], v169 offset:20480
	ds_read_b128 v[208:211], v169 offset:21504
	ds_read_b128 v[212:215], v169 offset:22528
	ds_read_b128 v[216:219], v169 offset:23552
	global_load_lds_dwordx4 v[164:165], off
	s_add_i32 m0, s82, 0x2000
	s_add_u32 s82, s48, 0x40000
	v_lshl_add_u64 v[220:221], s[48:49], 0, v[144:145]
	s_addc_u32 s83, s49, 0
	s_add_i32 s84, s71, s54
	global_load_lds_dwordx4 v[220:221], off
	v_lshl_add_u64 v[222:223], s[82:83], 0, v[148:149]
	s_mov_b32 m0, s84
	v_lshl_add_u64 v[224:225], s[50:51], 0, v[146:147]
	global_load_lds_dwordx4 v[222:223], off
	v_lshl_add_u64 v[222:223], s[82:83], 0, v[144:145]
	s_add_i32 m0, s84, 0x2000
	s_nop 0
	global_load_lds_dwordx4 v[222:223], off
	v_lshl_add_u64 v[222:223], s[50:51], 0, v[150:151]
	s_mov_b32 m0, s57
	s_nop 0
	global_load_lds_dwordx4 v[222:223], off
	s_mov_b32 m0, s58
	s_nop 0
	global_load_lds_dwordx4 v[224:225], off
	s_waitcnt vmcnt(8)
	s_waitcnt lgkmcnt(0)
	s_barrier
; #define PG8_STAGE(bufoff, gbase, voff) do { _Pragma("unroll") for (int _i = 0; _i < 2; ++_i) \
;         __builtin_amdgcn_global_load_lds((const unsigned*)((const char*)(gbase) + (voff)[_i]), (LAS unsigned*)(lds + (bufoff) + ldsw + _i * 8192), 16, 0, 0); } while (0)
; #define PG8_LDA(dst, b, h) do { _Pragma("unroll") for (int m = 0; m < 4; ++m) _Pragma("unroll") for (int k = 0; k < 2; ++k) dst[m][k] = *(const LAS bf16x8*)(lds + PG8_SA(b, h) + aoff + m * 2048 + k * 1024); } while (0)
; #define PG8_LDB(dst, b, h) do { _Pragma("unroll") for (int n = 0; n < 2; ++n) _Pragma("unroll") for (int k = 0; k < 2; ++k) dst[n][k] = *(const LAS bf16x8*)(lds + PG8_SB(b, h) + boff + n * 2048 + k * 1024); } while (0)
; #define PG8_MMA(ai, bj, At, Bt) do { __builtin_amdgcn_s_setprio(1); _Pragma("unroll") for (int m = 0; m < 4; ++m) _Pragma("unroll") for (int n = 0; n < 2; ++n) _Pragma("unroll") for (int k = 0; k < 2; ++k) \
;         acc[ai][bj][m][n] = __builtin_amdgcn_mfma_f32_16x16x32_bf16(Bt[n][k], At[m][k], acc[ai][bj][m][n], 0, 0, 0); __builtin_amdgcn_s_setprio(0); } while (0)
; #define PG8_WAIT_V(n) asm volatile("s_waitcnt vmcnt(" #n ")" ::: "memory")
; #define PG8_WAIT_L(n) asm volatile("s_waitcnt lgkmcnt(" #n ")" ::: "memory")
; #define PG8_BAR __builtin_amdgcn_s_barrier()
; #define PG8_SCHED __builtin_amdgcn_sched_barrier(0)
; template <class Epi, class Sched>
; __device__ __forceinline__ void gemm_phase(LAS unsigned char* lds, const Gemm g, const Sched& S, const Epi& E, const int wid) {
;     ...
;             PG8_WAIT_V(8); PG8_WAIT_L(0); PG8_BAR; PG8_MMA(1, 0, At, B0); PG8_MMA(1, 1, At, B1); PG8_BAR; PG8_SCHED;
;             PG8_LDB(B0, 1, 0); PG8_LDB(B1, 1, 1); PG8_SCHED; PG8_LDA(At, 1, 0); PG8_STAGE(PG8_SA(0, 1), a2 + hstepA, voffA);
;             PG8_WAIT_V(8); PG8_WAIT_L(0); PG8_BAR; PG8_MMA(0, 0, At, B0); PG8_MMA(0, 1, At, B1); PG8_BAR; PG8_SCHED;
	s_setprio 1
	s_waitcnt lgkmcnt(0)
	v_mfma_f32_16x16x32_bf16 v[60:63], v[128:131], v[188:191], v[60:63]
	v_mfma_f32_16x16x32_bf16 v[56:59], v[136:139], v[188:191], v[56:59]
	v_mfma_f32_16x16x32_bf16 v[48:51], v[128:131], v[196:199], v[48:51]
	v_mfma_f32_16x16x32_bf16 v[40:43], v[136:139], v[196:199], v[40:43]
	v_mfma_f32_16x16x32_bf16 v[32:35], v[128:131], v[204:207], v[32:35]
	v_mfma_f32_16x16x32_bf16 v[24:27], v[136:139], v[204:207], v[24:27]
	v_mfma_f32_16x16x32_bf16 v[16:19], v[128:131], v[212:215], v[16:19]
	v_mfma_f32_16x16x32_bf16 v[8:11], v[136:139], v[212:215], v[8:11]
	v_mfma_f32_16x16x32_bf16 v[60:63], v[132:135], v[192:195], v[60:63]
	v_mfma_f32_16x16x32_bf16 v[56:59], v[140:143], v[192:195], v[56:59]
	v_mfma_f32_16x16x32_bf16 v[48:51], v[132:135], v[200:203], v[48:51]
	v_mfma_f32_16x16x32_bf16 v[40:43], v[140:143], v[200:203], v[40:43]
	v_mfma_f32_16x16x32_bf16 v[32:35], v[132:135], v[208:211], v[32:35]
	v_mfma_f32_16x16x32_bf16 v[24:27], v[140:143], v[208:211], v[24:27]
	v_mfma_f32_16x16x32_bf16 v[16:19], v[132:135], v[216:219], v[16:19]
	v_mfma_f32_16x16x32_bf16 v[8:11], v[140:143], v[216:219], v[8:11]
	v_mfma_f32_16x16x32_bf16 v[52:55], v[172:175], v[188:191], v[52:55]
	v_mfma_f32_16x16x32_bf16 v[44:47], v[180:183], v[188:191], v[44:47]
	v_mfma_f32_16x16x32_bf16 v[36:39], v[172:175], v[196:199], v[36:39]
	v_mfma_f32_16x16x32_bf16 v[28:31], v[180:183], v[196:199], v[28:31]
	v_mfma_f32_16x16x32_bf16 v[20:23], v[172:175], v[204:207], v[20:23]
	v_mfma_f32_16x16x32_bf16 v[12:15], v[180:183], v[204:207], v[12:15]
	v_mfma_f32_16x16x32_bf16 v[4:7], v[172:175], v[212:215], v[4:7]
	v_mfma_f32_16x16x32_bf16 v[0:3], v[180:183], v[212:215], v[0:3]
	v_mfma_f32_16x16x32_bf16 v[52:55], v[176:179], v[192:195], v[52:55]
	v_mfma_f32_16x16x32_bf16 v[44:47], v[184:187], v[192:195], v[44:47]
	v_mfma_f32_16x16x32_bf16 v[36:39], v[176:179], v[200:203], v[36:39]
	v_mfma_f32_16x16x32_bf16 v[28:31], v[184:187], v[200:203], v[28:31]
	v_mfma_f32_16x16x32_bf16 v[20:23], v[176:179], v[208:211], v[20:23]
	v_mfma_f32_16x16x32_bf16 v[12:15], v[184:187], v[208:211], v[12:15]
	v_mfma_f32_16x16x32_bf16 v[4:7], v[176:179], v[216:219], v[4:7]
	v_mfma_f32_16x16x32_bf16 v[0:3], v[184:187], v[216:219], v[0:3]
	s_setprio 0
	s_barrier
	s_add_i32 s82, 0, 0x18000
	s_add_i32 s83, 0, 0x1c000
	v_add_u32_e32 v140, s82, v166
	v_add_u32_e32 v152, s83, v166
	ds_read_b128 v[128:131], v140
	ds_read_b128 v[132:135], v140 offset:1024
	ds_read_b128 v[136:139], v140 offset:2048
	ds_read_b128 v[140:143], v140 offset:3072
	ds_read_b128 v[172:175], v152
	ds_read_b128 v[176:179], v152 offset:1024
	ds_read_b128 v[180:183], v152 offset:2048
	ds_read_b128 v[184:187], v152 offset:3072
	s_add_u32 s50, s50, 0x40000
	s_addc_u32 s51, s51, 0
	s_mov_b32 m0, s59
	v_lshl_add_u64 v[226:227], s[50:51], 0, v[150:151]
	ds_read_b128 v[188:191], v169 offset:32768
	ds_read_b128 v[192:195], v169 offset:33792
	ds_read_b128 v[196:199], v169 offset:34816
	ds_read_b128 v[200:203], v169 offset:35840
	ds_read_b128 v[204:207], v169 offset:36864
	ds_read_b128 v[208:211], v169 offset:37888
	ds_read_b128 v[212:215], v169 offset:38912
	ds_read_b128 v[216:219], v169 offset:39936
	global_load_lds_dwordx4 v[226:227], off
	v_lshl_add_u64 v[226:227], s[50:51], 0, v[146:147]
	s_mov_b32 m0, s60
	s_nop 0
	global_load_lds_dwordx4 v[226:227], off
	s_waitcnt vmcnt(8)
	s_waitcnt lgkmcnt(0)
	s_barrier
	s_setprio 1
	s_waitcnt lgkmcnt(0)
	v_mfma_f32_16x16x32_bf16 v[124:127], v[128:131], v[188:191], v[124:127]
	v_mfma_f32_16x16x32_bf16 v[120:123], v[136:139], v[188:191], v[120:123]
	v_mfma_f32_16x16x32_bf16 v[116:119], v[128:131], v[196:199], v[116:119]
	v_mfma_f32_16x16x32_bf16 v[112:115], v[136:139], v[196:199], v[112:115]
	v_mfma_f32_16x16x32_bf16 v[108:111], v[128:131], v[204:207], v[108:111]
	v_mfma_f32_16x16x32_bf16 v[96:99], v[136:139], v[204:207], v[96:99]
	v_mfma_f32_16x16x32_bf16 v[80:83], v[128:131], v[212:215], v[80:83]
	v_mfma_f32_16x16x32_bf16 v[72:75], v[136:139], v[212:215], v[72:75]
	v_mfma_f32_16x16x32_bf16 v[124:127], v[132:135], v[192:195], v[124:127]
	v_mfma_f32_16x16x32_bf16 v[120:123], v[140:143], v[192:195], v[120:123]
	v_mfma_f32_16x16x32_bf16 v[116:119], v[132:135], v[200:203], v[116:119]
	v_mfma_f32_16x16x32_bf16 v[112:115], v[140:143], v[200:203], v[112:115]
	v_mfma_f32_16x16x32_bf16 v[108:111], v[132:135], v[208:211], v[108:111]
	v_mfma_f32_16x16x32_bf16 v[96:99], v[140:143], v[208:211], v[96:99]
	v_mfma_f32_16x16x32_bf16 v[80:83], v[132:135], v[216:219], v[80:83]
	v_mfma_f32_16x16x32_bf16 v[72:75], v[140:143], v[216:219], v[72:75]
	v_mfma_f32_16x16x32_bf16 v[104:107], v[172:175], v[188:191], v[104:107]
	v_mfma_f32_16x16x32_bf16 v[100:103], v[180:183], v[188:191], v[100:103]
	v_mfma_f32_16x16x32_bf16 v[92:95], v[172:175], v[196:199], v[92:95]
	v_mfma_f32_16x16x32_bf16 v[88:91], v[180:183], v[196:199], v[88:91]
	v_mfma_f32_16x16x32_bf16 v[84:87], v[172:175], v[204:207], v[84:87]
	v_mfma_f32_16x16x32_bf16 v[76:79], v[180:183], v[204:207], v[76:79]
	v_mfma_f32_16x16x32_bf16 v[68:71], v[172:175], v[212:215], v[68:71]
	v_mfma_f32_16x16x32_bf16 v[64:67], v[180:183], v[212:215], v[64:67]
	v_mfma_f32_16x16x32_bf16 v[104:107], v[176:179], v[192:195], v[104:107]
	v_mfma_f32_16x16x32_bf16 v[100:103], v[184:187], v[192:195], v[100:103]
	v_mfma_f32_16x16x32_bf16 v[92:95], v[176:179], v[200:203], v[92:95]
	v_mfma_f32_16x16x32_bf16 v[88:91], v[184:187], v[200:203], v[88:91]
	v_mfma_f32_16x16x32_bf16 v[84:87], v[176:179], v[208:211], v[84:87]
	v_mfma_f32_16x16x32_bf16 v[76:79], v[184:187], v[208:211], v[76:79]
	v_mfma_f32_16x16x32_bf16 v[68:71], v[176:179], v[216:219], v[68:71]
	v_mfma_f32_16x16x32_bf16 v[64:67], v[184:187], v[216:219], v[64:67]
	s_setprio 0
	s_barrier
; #define PG8_STAGE(bufoff, gbase, voff) do { _Pragma("unroll") for (int _i = 0; _i < 2; ++_i) \
;         __builtin_amdgcn_global_load_lds((const unsigned*)((const char*)(gbase) + (voff)[_i]), (LAS unsigned*)(lds + (bufoff) + ldsw + _i * 8192), 16, 0, 0); } while (0)
; #define PG8_LDA(dst, b, h) do { _Pragma("unroll") for (int m = 0; m < 4; ++m) _Pragma("unroll") for (int k = 0; k < 2; ++k) dst[m][k] = *(const LAS bf16x8*)(lds + PG8_SA(b, h) + aoff + m * 2048 + k * 1024); } while (0)
; #define PG8_MMA(ai, bj, At, Bt) do { __builtin_amdgcn_s_setprio(1); _Pragma("unroll") for (int m = 0; m < 4; ++m) _Pragma("unroll") for (int n = 0; n < 2; ++n) _Pragma("unroll") for (int k = 0; k < 2; ++k) \
;         acc[ai][bj][m][n] = __builtin_amdgcn_mfma_f32_16x16x32_bf16(Bt[n][k], At[m][k], acc[ai][bj][m][n], 0, 0, 0); __builtin_amdgcn_s_setprio(0); } while (0)
; #define PG8_WAIT_V(n) asm volatile("s_waitcnt vmcnt(" #n ")" ::: "memory")
; #define PG8_WAIT_L(n) asm volatile("s_waitcnt lgkmcnt(" #n ")" ::: "memory")
; #define PG8_BAR __builtin_amdgcn_s_barrier()
; #define PG8_SCHED __builtin_amdgcn_sched_barrier(0)
; template <class Epi, class Sched>
; __device__ __forceinline__ void gemm_phase(LAS unsigned char* lds, const Gemm g, const Sched& S, const Epi& E, const int wid) {
;     ...
;             PG8_LDA(At, 1, 1); PG8_STAGE(PG8_SB(1, 0), b3, voffB); PG8_STAGE(PG8_SB(1, 1), b3 + hstepB, voffB); PG8_STAGE(PG8_SA(1, 0), a3, voffA);
;             PG8_WAIT_V(8); PG8_WAIT_L(0); PG8_BAR; PG8_MMA(1, 0, At, B0); PG8_MMA(1, 1, At, B1); PG8_BAR; PG8_SCHED;
;         }
;         if (wr == 0) PG8_BAR;
	s_add_i32 s50, s82, s54
	v_lshl_add_u64 v[164:165], v[164:165], 0, s[16:17]
	s_mov_b32 m0, s50
	ds_read_b128 v[188:191], v169 offset:49152
	ds_read_b128 v[192:195], v169 offset:50176
	ds_read_b128 v[196:199], v169 offset:51200
	ds_read_b128 v[200:203], v169 offset:52224
	ds_read_b128 v[204:207], v169 offset:53248
	ds_read_b128 v[208:211], v169 offset:54272
	ds_read_b128 v[212:215], v169 offset:55296
	ds_read_b128 v[216:219], v169 offset:56320
	global_load_lds_dwordx4 v[164:165], off
	s_add_i32 m0, s50, 0x2000
	s_add_u32 s48, s48, 0x40080
	v_lshl_add_u64 v[164:165], v[220:221], 0, s[16:17]
	s_addc_u32 s49, s49, 0
	s_add_i32 s50, s83, s54
	global_load_lds_dwordx4 v[164:165], off
	v_lshl_add_u64 v[164:165], s[48:49], 0, v[148:149]
	s_mov_b32 m0, s50
	s_nop 0
	global_load_lds_dwordx4 v[164:165], off
	v_lshl_add_u64 v[164:165], s[48:49], 0, v[144:145]
	s_add_i32 m0, s50, 0x2000
	s_nop 0
	global_load_lds_dwordx4 v[164:165], off
	v_lshl_add_u64 v[164:165], v[222:223], 0, s[16:17]
	s_mov_b32 m0, s66
	s_nop 0
	global_load_lds_dwordx4 v[164:165], off
	v_lshl_add_u64 v[164:165], v[224:225], 0, s[16:17]
	s_mov_b32 m0, s67
	s_nop 0
	global_load_lds_dwordx4 v[164:165], off
	s_waitcnt vmcnt(8)
	s_waitcnt lgkmcnt(0)
	s_barrier
	s_setprio 1
	s_waitcnt lgkmcnt(0)
	v_mfma_f32_16x16x32_bf16 v[60:63], v[128:131], v[188:191], v[60:63]
	v_mfma_f32_16x16x32_bf16 v[56:59], v[136:139], v[188:191], v[56:59]
	v_mfma_f32_16x16x32_bf16 v[48:51], v[128:131], v[196:199], v[48:51]
	v_mfma_f32_16x16x32_bf16 v[40:43], v[136:139], v[196:199], v[40:43]
	v_mfma_f32_16x16x32_bf16 v[32:35], v[128:131], v[204:207], v[32:35]
	v_mfma_f32_16x16x32_bf16 v[24:27], v[136:139], v[204:207], v[24:27]
	v_mfma_f32_16x16x32_bf16 v[16:19], v[128:131], v[212:215], v[16:19]
	v_mfma_f32_16x16x32_bf16 v[8:11], v[136:139], v[212:215], v[8:11]
	v_mfma_f32_16x16x32_bf16 v[60:63], v[132:135], v[192:195], v[60:63]
	v_mfma_f32_16x16x32_bf16 v[56:59], v[140:143], v[192:195], v[56:59]
	v_mfma_f32_16x16x32_bf16 v[48:51], v[132:135], v[200:203], v[48:51]
	v_mfma_f32_16x16x32_bf16 v[40:43], v[140:143], v[200:203], v[40:43]
	v_mfma_f32_16x16x32_bf16 v[32:35], v[132:135], v[208:211], v[32:35]
	v_mfma_f32_16x16x32_bf16 v[24:27], v[140:143], v[208:211], v[24:27]
	v_mfma_f32_16x16x32_bf16 v[16:19], v[132:135], v[216:219], v[16:19]
	v_mfma_f32_16x16x32_bf16 v[8:11], v[140:143], v[216:219], v[8:11]
	v_mfma_f32_16x16x32_bf16 v[52:55], v[172:175], v[188:191], v[52:55]
	v_mfma_f32_16x16x32_bf16 v[44:47], v[180:183], v[188:191], v[44:47]
	v_mfma_f32_16x16x32_bf16 v[36:39], v[172:175], v[196:199], v[36:39]
	v_mfma_f32_16x16x32_bf16 v[28:31], v[180:183], v[196:199], v[28:31]
	v_mfma_f32_16x16x32_bf16 v[20:23], v[172:175], v[204:207], v[20:23]
	v_mfma_f32_16x16x32_bf16 v[12:15], v[180:183], v[204:207], v[12:15]
	v_mfma_f32_16x16x32_bf16 v[4:7], v[172:175], v[212:215], v[4:7]
	v_mfma_f32_16x16x32_bf16 v[0:3], v[180:183], v[212:215], v[0:3]
	v_mfma_f32_16x16x32_bf16 v[52:55], v[176:179], v[192:195], v[52:55]
	v_mfma_f32_16x16x32_bf16 v[44:47], v[184:187], v[192:195], v[44:47]
	v_mfma_f32_16x16x32_bf16 v[36:39], v[176:179], v[200:203], v[36:39]
	v_mfma_f32_16x16x32_bf16 v[28:31], v[184:187], v[200:203], v[28:31]
	v_mfma_f32_16x16x32_bf16 v[20:23], v[176:179], v[208:211], v[20:23]
	v_mfma_f32_16x16x32_bf16 v[12:15], v[184:187], v[208:211], v[12:15]
	v_mfma_f32_16x16x32_bf16 v[4:7], v[176:179], v[216:219], v[4:7]
	v_mfma_f32_16x16x32_bf16 v[0:3], v[184:187], v[216:219], v[0:3]
	s_setprio 0
	s_barrier
	s_add_i32 s81, s81, 2
	s_add_u32 s46, s46, 0x100
	s_addc_u32 s47, s47, 0
	s_add_u32 s79, s79, 0x100
	s_addc_u32 s80, s80, 0
	s_cmp_gt_u32 s81, 13
	s_cbranch_scc0 .LBB0_546
	s_and_b64 vcc, exec, s[18:19]
	s_cbranch_vccz .LBB0_549
	s_barrier

; #define PG8_STAGE(bufoff, gbase, voff) do { _Pragma("unroll") for (int _i = 0; _i < 2; ++_i) \
;         __builtin_amdgcn_global_load_lds((const unsigned*)((const char*)(gbase) + (voff)[_i]), (LAS unsigned*)(lds + (bufoff) + ldsw + _i * 8192), 16, 0, 0); } while (0)
; #define PG8_LDA(dst, b, h) do { _Pragma("unroll") for (int m = 0; m < 4; ++m) _Pragma("unroll") for (int k = 0; k < 2; ++k) dst[m][k] = *(const LAS bf16x8*)(lds + PG8_SA(b, h) + aoff + m * 2048 + k * 1024); } while (0)
; #define PG8_LDB(dst, b, h) do { _Pragma("unroll") for (int n = 0; n < 2; ++n) _Pragma("unroll") for (int k = 0; k < 2; ++k) dst[n][k] = *(const LAS bf16x8*)(lds + PG8_SB(b, h) + boff + n * 2048 + k * 1024); } while (0)
; #define PG8_MMA(ai, bj, At, Bt) do { __builtin_amdgcn_s_setprio(1); _Pragma("unroll") for (int m = 0; m < 4; ++m) _Pragma("unroll") for (int n = 0; n < 2; ++n) _Pragma("unroll") for (int k = 0; k < 2; ++k) \
;         acc[ai][bj][m][n] = __builtin_amdgcn_mfma_f32_16x16x32_bf16(Bt[n][k], At[m][k], acc[ai][bj][m][n], 0, 0, 0); __builtin_amdgcn_s_setprio(0); } while (0)
; #define PG8_WAIT_V(n) asm volatile("s_waitcnt vmcnt(" #n ")" ::: "memory")
; #define PG8_WAIT_L(n) asm volatile("s_waitcnt lgkmcnt(" #n ")" ::: "memory")
; #define PG8_BAR __builtin_amdgcn_s_barrier()
; #define PG8_SCHED __builtin_amdgcn_sched_barrier(0)
; template <class Epi, class Sched>
; __device__ __forceinline__ void gemm_phase(LAS unsigned char* lds, const Gemm g, const Sched& S, const Epi& E, const int wid) {
;     ...
;             const bool last = (t == nt - 2);
;             const char* a1 = cA + (size_t)(t + 1) * kstep;
;             const char* a2 = last ? nA : cA + (size_t)(t + 2) * kstep; const char* b2 = last ? nB : cB + (size_t)(t + 2) * kstep;
;             const char* a3 = a2 + kstep; const char* b3 = b2 + kstep;
;             PG8_LDB(B0, 0, 0); PG8_LDB(B1, 0, 1); PG8_SCHED; PG8_LDA(At, 0, 0); PG8_STAGE(PG8_SA(1, 1), a1 + hstepA, voffA);
;             PG8_WAIT_V(8); PG8_WAIT_L(0); PG8_BAR; PG8_MMA(0, 0, At, B0); PG8_MMA(0, 1, At, B1); PG8_BAR; PG8_SCHED;
;             PG8_LDA(At, 0, 1); PG8_STAGE(PG8_SB(0, 0), b2, voffB); PG8_STAGE(PG8_SB(0, 1), b2 + hstepB, voffB); PG8_STAGE(PG8_SA(0, 0), a2, voffA);
;             PG8_WAIT_V(8); PG8_WAIT_L(0); PG8_BAR; PG8_MMA(1, 0, At, B0); PG8_MMA(1, 1, At, B1); PG8_BAR; PG8_SCHED;
.LBB0_680:
	ds_read_b128 v[128:131], v235
	ds_read_b128 v[132:135], v235 offset:1024
	ds_read_b128 v[136:139], v235 offset:2048
	ds_read_b128 v[140:143], v235 offset:3072
	ds_read_b128 v[144:147], v236
	ds_read_b128 v[148:151], v236 offset:1024
	ds_read_b128 v[152:155], v236 offset:2048
	ds_read_b128 v[156:159], v236 offset:3072
	s_add_u32 s34, s30, 0xfffc0080
	s_addc_u32 s35, s31, -1
	s_cmp_eq_u32 s63, 12
	s_cselect_b32 s37, s21, s35
	s_cselect_b32 s36, s59, s34
	s_cselect_b32 s35, s19, s62
	s_cselect_b32 s34, s60, s61
	v_lshl_add_u64 v[192:193], s[30:31], 0, v[214:215]
	s_add_i32 m0, s44, 0xc000
	ds_read_b128 v[160:163], v237
	ds_read_b128 v[164:167], v237 offset:1024
	ds_read_b128 v[168:171], v237 offset:2048
	ds_read_b128 v[172:175], v237 offset:3072
	ds_read_b128 v[176:179], v237 offset:4096
	ds_read_b128 v[180:183], v237 offset:5120
	ds_read_b128 v[184:187], v237 offset:6144
	ds_read_b128 v[188:191], v237 offset:7168
	global_load_lds_dwordx4 v[192:193], off
	v_lshl_add_u64 v[192:193], s[30:31], 0, v[216:217]
	s_add_i32 m0, s44, 0xe000
	s_nop 0
	global_load_lds_dwordx4 v[192:193], off
	s_waitcnt vmcnt(8)
	s_waitcnt lgkmcnt(0)
	s_barrier
	s_setprio 1
	s_waitcnt lgkmcnt(0)
	v_mfma_f32_16x16x32_bf16 v[124:127], v[128:131], v[160:163], v[124:127]
	v_mfma_f32_16x16x32_bf16 v[120:123], v[136:139], v[160:163], v[120:123]
	v_mfma_f32_16x16x32_bf16 v[112:115], v[128:131], v[168:171], v[112:115]
	v_mfma_f32_16x16x32_bf16 v[104:107], v[136:139], v[168:171], v[104:107]
	v_mfma_f32_16x16x32_bf16 v[96:99], v[128:131], v[176:179], v[96:99]
	v_mfma_f32_16x16x32_bf16 v[88:91], v[136:139], v[176:179], v[88:91]
	v_mfma_f32_16x16x32_bf16 v[76:79], v[128:131], v[184:187], v[76:79]
	v_mfma_f32_16x16x32_bf16 v[72:75], v[136:139], v[184:187], v[72:75]
	v_mfma_f32_16x16x32_bf16 v[124:127], v[132:135], v[164:167], v[124:127]
	v_mfma_f32_16x16x32_bf16 v[120:123], v[140:143], v[164:167], v[120:123]
	v_mfma_f32_16x16x32_bf16 v[112:115], v[132:135], v[172:175], v[112:115]
	v_mfma_f32_16x16x32_bf16 v[104:107], v[140:143], v[172:175], v[104:107]
	v_mfma_f32_16x16x32_bf16 v[96:99], v[132:135], v[180:183], v[96:99]
	v_mfma_f32_16x16x32_bf16 v[88:91], v[140:143], v[180:183], v[88:91]
	v_mfma_f32_16x16x32_bf16 v[76:79], v[132:135], v[188:191], v[76:79]
	v_mfma_f32_16x16x32_bf16 v[72:75], v[140:143], v[188:191], v[72:75]
	v_mfma_f32_16x16x32_bf16 v[116:119], v[144:147], v[160:163], v[116:119]
	v_mfma_f32_16x16x32_bf16 v[108:111], v[152:155], v[160:163], v[108:111]
	v_mfma_f32_16x16x32_bf16 v[100:103], v[144:147], v[168:171], v[100:103]
	v_mfma_f32_16x16x32_bf16 v[92:95], v[152:155], v[168:171], v[92:95]
	v_mfma_f32_16x16x32_bf16 v[84:87], v[144:147], v[176:179], v[84:87]
	v_mfma_f32_16x16x32_bf16 v[80:83], v[152:155], v[176:179], v[80:83]
	v_mfma_f32_16x16x32_bf16 v[68:71], v[144:147], v[184:187], v[68:71]
	v_mfma_f32_16x16x32_bf16 v[64:67], v[152:155], v[184:187], v[64:67]
	v_mfma_f32_16x16x32_bf16 v[116:119], v[148:151], v[164:167], v[116:119]
	v_mfma_f32_16x16x32_bf16 v[108:111], v[156:159], v[164:167], v[108:111]
	v_mfma_f32_16x16x32_bf16 v[100:103], v[148:151], v[172:175], v[100:103]
	v_mfma_f32_16x16x32_bf16 v[92:95], v[156:159], v[172:175], v[92:95]
	v_mfma_f32_16x16x32_bf16 v[84:87], v[148:151], v[180:183], v[84:87]
	v_mfma_f32_16x16x32_bf16 v[80:83], v[156:159], v[180:183], v[80:83]
	v_mfma_f32_16x16x32_bf16 v[68:71], v[148:151], v[188:191], v[68:71]
	v_mfma_f32_16x16x32_bf16 v[64:67], v[156:159], v[188:191], v[64:67]
	s_setprio 0
	s_barrier
	s_add_i32 s64, s51, s41
	v_lshl_add_u64 v[192:193], s[34:35], 0, v[210:211]
	s_mov_b32 m0, s64
	ds_read_b128 v[160:163], v237 offset:16384
	ds_read_b128 v[164:167], v237 offset:17408
	ds_read_b128 v[168:171], v237 offset:18432
	ds_read_b128 v[172:175], v237 offset:19456
	ds_read_b128 v[176:179], v237 offset:20480
	ds_read_b128 v[180:183], v237 offset:21504
	ds_read_b128 v[184:187], v237 offset:22528
	ds_read_b128 v[188:191], v237 offset:23552
	global_load_lds_dwordx4 v[192:193], off
	s_add_i32 m0, s64, 0x2000
	s_add_u32 s64, s34, 0x40000
	v_lshl_add_u64 v[194:195], s[34:35], 0, v[208:209]
	s_addc_u32 s65, s35, 0
	s_add_i32 s66, s52, s41
	global_load_lds_dwordx4 v[194:195], off
	v_lshl_add_u64 v[196:197], s[64:65], 0, v[210:211]
	s_mov_b32 m0, s66
	v_lshl_add_u64 v[198:199], s[36:37], 0, v[208:209]
	global_load_lds_dwordx4 v[196:197], off
	v_lshl_add_u64 v[196:197], s[64:65], 0, v[208:209]
	s_add_i32 m0, s66, 0x2000
	s_nop 0
	global_load_lds_dwordx4 v[196:197], off
	v_lshl_add_u64 v[196:197], s[36:37], 0, v[210:211]
	s_mov_b32 m0, s44
	s_nop 0
	global_load_lds_dwordx4 v[196:197], off
	s_mov_b32 m0, s45
	s_nop 0
	global_load_lds_dwordx4 v[198:199], off
	s_waitcnt vmcnt(8)
	s_waitcnt lgkmcnt(0)
	s_barrier
; #define PG8_STAGE(bufoff, gbase, voff) do { _Pragma("unroll") for (int _i = 0; _i < 2; ++_i) \
;         __builtin_amdgcn_global_load_lds((const unsigned*)((const char*)(gbase) + (voff)[_i]), (LAS unsigned*)(lds + (bufoff) + ldsw + _i * 8192), 16, 0, 0); } while (0)
; #define PG8_LDA(dst, b, h) do { _Pragma("unroll") for (int m = 0; m < 4; ++m) _Pragma("unroll") for (int k = 0; k < 2; ++k) dst[m][k] = *(const LAS bf16x8*)(lds + PG8_SA(b, h) + aoff + m * 2048 + k * 1024); } while (0)
; #define PG8_LDB(dst, b, h) do { _Pragma("unroll") for (int n = 0; n < 2; ++n) _Pragma("unroll") for (int k = 0; k < 2; ++k) dst[n][k] = *(const LAS bf16x8*)(lds + PG8_SB(b, h) + boff + n * 2048 + k * 1024); } while (0)
; #define PG8_MMA(ai, bj, At, Bt) do { __builtin_amdgcn_s_setprio(1); _Pragma("unroll") for (int m = 0; m < 4; ++m) _Pragma("unroll") for (int n = 0; n < 2; ++n) _Pragma("unroll") for (int k = 0; k < 2; ++k) \
;         acc[ai][bj][m][n] = __builtin_amdgcn_mfma_f32_16x16x32_bf16(Bt[n][k], At[m][k], acc[ai][bj][m][n], 0, 0, 0); __builtin_amdgcn_s_setprio(0); } while (0)
; #define PG8_WAIT_V(n) asm volatile("s_waitcnt vmcnt(" #n ")" ::: "memory")
; #define PG8_WAIT_L(n) asm volatile("s_waitcnt lgkmcnt(" #n ")" ::: "memory")
; #define PG8_BAR __builtin_amdgcn_s_barrier()
; #define PG8_SCHED __builtin_amdgcn_sched_barrier(0)
; template <class Epi, class Sched>
; __device__ __forceinline__ void gemm_phase(LAS unsigned char* lds, const Gemm g, const Sched& S, const Epi& E, const int wid) {
;     ...
;             PG8_WAIT_V(8); PG8_WAIT_L(0); PG8_BAR; PG8_MMA(1, 0, At, B0); PG8_MMA(1, 1, At, B1); PG8_BAR; PG8_SCHED;
;             PG8_LDB(B0, 1, 0); PG8_LDB(B1, 1, 1); PG8_SCHED; PG8_LDA(At, 1, 0); PG8_STAGE(PG8_SA(0, 1), a2 + hstepA, voffA);
;             PG8_WAIT_V(8); PG8_WAIT_L(0); PG8_BAR; PG8_MMA(0, 0, At, B0); PG8_MMA(0, 1, At, B1); PG8_BAR; PG8_SCHED;
	s_setprio 1
	s_waitcnt lgkmcnt(0)
	v_mfma_f32_16x16x32_bf16 v[60:63], v[128:131], v[160:163], v[60:63]
	v_mfma_f32_16x16x32_bf16 v[56:59], v[136:139], v[160:163], v[56:59]
	v_mfma_f32_16x16x32_bf16 v[48:51], v[128:131], v[168:171], v[48:51]
	v_mfma_f32_16x16x32_bf16 v[40:43], v[136:139], v[168:171], v[40:43]
	v_mfma_f32_16x16x32_bf16 v[32:35], v[128:131], v[176:179], v[32:35]
	v_mfma_f32_16x16x32_bf16 v[24:27], v[136:139], v[176:179], v[24:27]
	v_mfma_f32_16x16x32_bf16 v[12:15], v[128:131], v[184:187], v[12:15]
	v_mfma_f32_16x16x32_bf16 v[8:11], v[136:139], v[184:187], v[8:11]
	v_mfma_f32_16x16x32_bf16 v[60:63], v[132:135], v[164:167], v[60:63]
	v_mfma_f32_16x16x32_bf16 v[56:59], v[140:143], v[164:167], v[56:59]
	v_mfma_f32_16x16x32_bf16 v[48:51], v[132:135], v[172:175], v[48:51]
	v_mfma_f32_16x16x32_bf16 v[40:43], v[140:143], v[172:175], v[40:43]
	v_mfma_f32_16x16x32_bf16 v[32:35], v[132:135], v[180:183], v[32:35]
	v_mfma_f32_16x16x32_bf16 v[24:27], v[140:143], v[180:183], v[24:27]
	v_mfma_f32_16x16x32_bf16 v[12:15], v[132:135], v[188:191], v[12:15]
	v_mfma_f32_16x16x32_bf16 v[8:11], v[140:143], v[188:191], v[8:11]
	v_mfma_f32_16x16x32_bf16 v[52:55], v[144:147], v[160:163], v[52:55]
	v_mfma_f32_16x16x32_bf16 v[44:47], v[152:155], v[160:163], v[44:47]
	v_mfma_f32_16x16x32_bf16 v[36:39], v[144:147], v[168:171], v[36:39]
	v_mfma_f32_16x16x32_bf16 v[28:31], v[152:155], v[168:171], v[28:31]
	v_mfma_f32_16x16x32_bf16 v[20:23], v[144:147], v[176:179], v[20:23]
	v_mfma_f32_16x16x32_bf16 v[16:19], v[152:155], v[176:179], v[16:19]
	v_mfma_f32_16x16x32_bf16 v[4:7], v[144:147], v[184:187], v[4:7]
	v_mfma_f32_16x16x32_bf16 v[0:3], v[152:155], v[184:187], v[0:3]
	v_mfma_f32_16x16x32_bf16 v[52:55], v[148:151], v[164:167], v[52:55]
	v_mfma_f32_16x16x32_bf16 v[44:47], v[156:159], v[164:167], v[44:47]
	v_mfma_f32_16x16x32_bf16 v[36:39], v[148:151], v[172:175], v[36:39]
	v_mfma_f32_16x16x32_bf16 v[28:31], v[156:159], v[172:175], v[28:31]
	v_mfma_f32_16x16x32_bf16 v[20:23], v[148:151], v[180:183], v[20:23]
	v_mfma_f32_16x16x32_bf16 v[16:19], v[156:159], v[180:183], v[16:19]
	v_mfma_f32_16x16x32_bf16 v[4:7], v[148:151], v[188:191], v[4:7]
	v_mfma_f32_16x16x32_bf16 v[0:3], v[156:159], v[188:191], v[0:3]
	s_setprio 0
	s_barrier
	s_add_i32 s64, 0, 0x18000
	s_add_i32 s65, 0, 0x1c000
	v_add_u32_e32 v140, s64, v233
	v_add_u32_e32 v156, s65, v233
	ds_read_b128 v[128:131], v140
	ds_read_b128 v[132:135], v140 offset:1024
	ds_read_b128 v[136:139], v140 offset:2048
	ds_read_b128 v[140:143], v140 offset:3072
	ds_read_b128 v[144:147], v156
	ds_read_b128 v[148:151], v156 offset:1024
	ds_read_b128 v[152:155], v156 offset:2048
	ds_read_b128 v[156:159], v156 offset:3072
	s_add_u32 s36, s36, 0x40000
	s_addc_u32 s37, s37, 0
	s_mov_b32 m0, s46
	v_lshl_add_u64 v[200:201], s[36:37], 0, v[210:211]
	ds_read_b128 v[160:163], v237 offset:32768
	ds_read_b128 v[164:167], v237 offset:33792
	ds_read_b128 v[168:171], v237 offset:34816
	ds_read_b128 v[172:175], v237 offset:35840
	ds_read_b128 v[176:179], v237 offset:36864
	ds_read_b128 v[180:183], v237 offset:37888
	ds_read_b128 v[184:187], v237 offset:38912
	ds_read_b128 v[188:191], v237 offset:39936
	global_load_lds_dwordx4 v[200:201], off
	v_lshl_add_u64 v[200:201], s[36:37], 0, v[208:209]
	s_mov_b32 m0, s47
	s_nop 0
	global_load_lds_dwordx4 v[200:201], off
	s_waitcnt vmcnt(8)
	s_waitcnt lgkmcnt(0)
	s_barrier
	s_setprio 1
	s_waitcnt lgkmcnt(0)
	v_mfma_f32_16x16x32_bf16 v[124:127], v[128:131], v[160:163], v[124:127]
	v_mfma_f32_16x16x32_bf16 v[120:123], v[136:139], v[160:163], v[120:123]
	v_mfma_f32_16x16x32_bf16 v[112:115], v[128:131], v[168:171], v[112:115]
	v_mfma_f32_16x16x32_bf16 v[104:107], v[136:139], v[168:171], v[104:107]
	v_mfma_f32_16x16x32_bf16 v[96:99], v[128:131], v[176:179], v[96:99]
	v_mfma_f32_16x16x32_bf16 v[88:91], v[136:139], v[176:179], v[88:91]
	v_mfma_f32_16x16x32_bf16 v[76:79], v[128:131], v[184:187], v[76:79]
	v_mfma_f32_16x16x32_bf16 v[72:75], v[136:139], v[184:187], v[72:75]
	v_mfma_f32_16x16x32_bf16 v[124:127], v[132:135], v[164:167], v[124:127]
	v_mfma_f32_16x16x32_bf16 v[120:123], v[140:143], v[164:167], v[120:123]
	v_mfma_f32_16x16x32_bf16 v[112:115], v[132:135], v[172:175], v[112:115]
	v_mfma_f32_16x16x32_bf16 v[104:107], v[140:143], v[172:175], v[104:107]
	v_mfma_f32_16x16x32_bf16 v[96:99], v[132:135], v[180:183], v[96:99]
	v_mfma_f32_16x16x32_bf16 v[88:91], v[140:143], v[180:183], v[88:91]
	v_mfma_f32_16x16x32_bf16 v[76:79], v[132:135], v[188:191], v[76:79]
	v_mfma_f32_16x16x32_bf16 v[72:75], v[140:143], v[188:191], v[72:75]
	v_mfma_f32_16x16x32_bf16 v[116:119], v[144:147], v[160:163], v[116:119]
	v_mfma_f32_16x16x32_bf16 v[108:111], v[152:155], v[160:163], v[108:111]
	v_mfma_f32_16x16x32_bf16 v[100:103], v[144:147], v[168:171], v[100:103]
	v_mfma_f32_16x16x32_bf16 v[92:95], v[152:155], v[168:171], v[92:95]
	v_mfma_f32_16x16x32_bf16 v[84:87], v[144:147], v[176:179], v[84:87]
	v_mfma_f32_16x16x32_bf16 v[80:83], v[152:155], v[176:179], v[80:83]
	v_mfma_f32_16x16x32_bf16 v[68:71], v[144:147], v[184:187], v[68:71]
	v_mfma_f32_16x16x32_bf16 v[64:67], v[152:155], v[184:187], v[64:67]
	v_mfma_f32_16x16x32_bf16 v[116:119], v[148:151], v[164:167], v[116:119]
	v_mfma_f32_16x16x32_bf16 v[108:111], v[156:159], v[164:167], v[108:111]
	v_mfma_f32_16x16x32_bf16 v[100:103], v[148:151], v[172:175], v[100:103]
	v_mfma_f32_16x16x32_bf16 v[92:95], v[156:159], v[172:175], v[92:95]
	v_mfma_f32_16x16x32_bf16 v[84:87], v[148:151], v[180:183], v[84:87]
	v_mfma_f32_16x16x32_bf16 v[80:83], v[156:159], v[180:183], v[80:83]
	v_mfma_f32_16x16x32_bf16 v[68:71], v[148:151], v[188:191], v[68:71]
	v_mfma_f32_16x16x32_bf16 v[64:67], v[156:159], v[188:191], v[64:67]
	s_setprio 0
	s_barrier
; #define PG8_STAGE(bufoff, gbase, voff) do { _Pragma("unroll") for (int _i = 0; _i < 2; ++_i) \
;         __builtin_amdgcn_global_load_lds((const unsigned*)((const char*)(gbase) + (voff)[_i]), (LAS unsigned*)(lds + (bufoff) + ldsw + _i * 8192), 16, 0, 0); } while (0)
; #define PG8_LDA(dst, b, h) do { _Pragma("unroll") for (int m = 0; m < 4; ++m) _Pragma("unroll") for (int k = 0; k < 2; ++k) dst[m][k] = *(const LAS bf16x8*)(lds + PG8_SA(b, h) + aoff + m * 2048 + k * 1024); } while (0)
; #define PG8_MMA(ai, bj, At, Bt) do { __builtin_amdgcn_s_setprio(1); _Pragma("unroll") for (int m = 0; m < 4; ++m) _Pragma("unroll") for (int n = 0; n < 2; ++n) _Pragma("unroll") for (int k = 0; k < 2; ++k) \
;         acc[ai][bj][m][n] = __builtin_amdgcn_mfma_f32_16x16x32_bf16(Bt[n][k], At[m][k], acc[ai][bj][m][n], 0, 0, 0); __builtin_amdgcn_s_setprio(0); } while (0)
; #define PG8_WAIT_V(n) asm volatile("s_waitcnt vmcnt(" #n ")" ::: "memory")
; #define PG8_WAIT_L(n) asm volatile("s_waitcnt lgkmcnt(" #n ")" ::: "memory")
; #define PG8_BAR __builtin_amdgcn_s_barrier()
; #define PG8_SCHED __builtin_amdgcn_sched_barrier(0)
; template <class Epi, class Sched>
; __device__ __forceinline__ void gemm_phase(LAS unsigned char* lds, const Gemm g, const Sched& S, const Epi& E, const int wid) {
;     ...
;             PG8_LDA(At, 1, 1); PG8_STAGE(PG8_SB(1, 0), b3, voffB); PG8_STAGE(PG8_SB(1, 1), b3 + hstepB, voffB); PG8_STAGE(PG8_SA(1, 0), a3, voffA);
;             PG8_WAIT_V(8); PG8_WAIT_L(0); PG8_BAR; PG8_MMA(1, 0, At, B0); PG8_MMA(1, 1, At, B1); PG8_BAR; PG8_SCHED;
;         }
;         if (wr == 0) PG8_BAR;
	s_add_i32 s36, s64, s41
	v_lshl_add_u64 v[192:193], v[192:193], 0, s[12:13]
	s_mov_b32 m0, s36
	ds_read_b128 v[160:163], v237 offset:49152
	ds_read_b128 v[164:167], v237 offset:50176
	ds_read_b128 v[168:171], v237 offset:51200
	ds_read_b128 v[172:175], v237 offset:52224
	ds_read_b128 v[176:179], v237 offset:53248
	ds_read_b128 v[180:183], v237 offset:54272
	ds_read_b128 v[184:187], v237 offset:55296
	ds_read_b128 v[188:191], v237 offset:56320
	global_load_lds_dwordx4 v[192:193], off
	s_add_i32 m0, s36, 0x2000
	s_add_u32 s34, s34, 0x40080
	v_lshl_add_u64 v[192:193], v[194:195], 0, s[12:13]
	s_addc_u32 s35, s35, 0
	s_add_i32 s36, s65, s41
	global_load_lds_dwordx4 v[192:193], off
	v_lshl_add_u64 v[192:193], s[34:35], 0, v[210:211]
	s_mov_b32 m0, s36
	s_nop 0
	global_load_lds_dwordx4 v[192:193], off
	v_lshl_add_u64 v[192:193], s[34:35], 0, v[208:209]
	s_add_i32 m0, s36, 0x2000
	s_nop 0
	global_load_lds_dwordx4 v[192:193], off
	v_lshl_add_u64 v[192:193], v[196:197], 0, s[12:13]
	s_mov_b32 m0, s33
	s_nop 0
	global_load_lds_dwordx4 v[192:193], off
	v_lshl_add_u64 v[192:193], v[198:199], 0, s[12:13]
	s_mov_b32 m0, s50
	s_nop 0
	global_load_lds_dwordx4 v[192:193], off
	s_waitcnt vmcnt(8)
	s_waitcnt lgkmcnt(0)
	s_barrier
	s_setprio 1
	s_waitcnt lgkmcnt(0)
	v_mfma_f32_16x16x32_bf16 v[60:63], v[128:131], v[160:163], v[60:63]
	v_mfma_f32_16x16x32_bf16 v[56:59], v[136:139], v[160:163], v[56:59]
	v_mfma_f32_16x16x32_bf16 v[48:51], v[128:131], v[168:171], v[48:51]
	v_mfma_f32_16x16x32_bf16 v[40:43], v[136:139], v[168:171], v[40:43]
	v_mfma_f32_16x16x32_bf16 v[32:35], v[128:131], v[176:179], v[32:35]
	v_mfma_f32_16x16x32_bf16 v[24:27], v[136:139], v[176:179], v[24:27]
	v_mfma_f32_16x16x32_bf16 v[12:15], v[128:131], v[184:187], v[12:15]
	v_mfma_f32_16x16x32_bf16 v[8:11], v[136:139], v[184:187], v[8:11]
	v_mfma_f32_16x16x32_bf16 v[60:63], v[132:135], v[164:167], v[60:63]
	v_mfma_f32_16x16x32_bf16 v[56:59], v[140:143], v[164:167], v[56:59]
	v_mfma_f32_16x16x32_bf16 v[48:51], v[132:135], v[172:175], v[48:51]
	v_mfma_f32_16x16x32_bf16 v[40:43], v[140:143], v[172:175], v[40:43]
	v_mfma_f32_16x16x32_bf16 v[32:35], v[132:135], v[180:183], v[32:35]
	v_mfma_f32_16x16x32_bf16 v[24:27], v[140:143], v[180:183], v[24:27]
	v_mfma_f32_16x16x32_bf16 v[12:15], v[132:135], v[188:191], v[12:15]
	v_mfma_f32_16x16x32_bf16 v[8:11], v[140:143], v[188:191], v[8:11]
	v_mfma_f32_16x16x32_bf16 v[52:55], v[144:147], v[160:163], v[52:55]
	v_mfma_f32_16x16x32_bf16 v[44:47], v[152:155], v[160:163], v[44:47]
	v_mfma_f32_16x16x32_bf16 v[36:39], v[144:147], v[168:171], v[36:39]
	v_mfma_f32_16x16x32_bf16 v[28:31], v[152:155], v[168:171], v[28:31]
	v_mfma_f32_16x16x32_bf16 v[20:23], v[144:147], v[176:179], v[20:23]
	v_mfma_f32_16x16x32_bf16 v[16:19], v[152:155], v[176:179], v[16:19]
	v_mfma_f32_16x16x32_bf16 v[4:7], v[144:147], v[184:187], v[4:7]
	v_mfma_f32_16x16x32_bf16 v[0:3], v[152:155], v[184:187], v[0:3]
	v_mfma_f32_16x16x32_bf16 v[52:55], v[148:151], v[164:167], v[52:55]
	v_mfma_f32_16x16x32_bf16 v[44:47], v[156:159], v[164:167], v[44:47]
	v_mfma_f32_16x16x32_bf16 v[36:39], v[148:151], v[172:175], v[36:39]
	v_mfma_f32_16x16x32_bf16 v[28:31], v[156:159], v[172:175], v[28:31]
	v_mfma_f32_16x16x32_bf16 v[20:23], v[148:151], v[180:183], v[20:23]
	v_mfma_f32_16x16x32_bf16 v[16:19], v[156:159], v[180:183], v[16:19]
	v_mfma_f32_16x16x32_bf16 v[4:7], v[148:151], v[188:191], v[4:7]
	v_mfma_f32_16x16x32_bf16 v[0:3], v[156:159], v[188:191], v[0:3]
	s_setprio 0
	s_barrier
	s_add_i32 s63, s63, 2
	s_add_u32 s30, s30, 0x100
	s_addc_u32 s31, s31, 0
	s_add_u32 s61, s61, 0x100
	s_addc_u32 s62, s62, 0
	s_cmp_gt_u32 s63, 13
	s_cbranch_scc0 .LBB0_680
	s_and_b64 vcc, exec, s[14:15]
	s_cbranch_vccz .LBB0_683
	s_barrier
